# E5 K-loop LDS-DMA addressing via SGPR base + 32-bit lane offset (no VALU 64-bit adds in load segments)
# speedup vs baseline: 1.0083x; 1.0083x over previous
.LBB0_225:
	ds_read_b128 v[128:131], v157
	ds_read_b128 v[132:135], v157 offset:1024
	ds_read_b128 v[146:149], v157 offset:2048
	ds_read_b128 v[164:167], v157 offset:3072
	ds_read_b128 v[168:171], v159
	ds_read_b128 v[172:175], v159 offset:1024
	ds_read_b128 v[176:179], v159 offset:2048
	ds_read_b128 v[180:183], v159 offset:3072
	s_add_u32 s36, s22, 0xfff80080
	s_addc_u32 s37, s23, -1
	s_cmp_eq_u32 s78, 28
	s_cselect_b32 s81, s5, s37
	s_cselect_b32 s80, s14, s36
	s_cselect_b32 vcc_hi, s20, s45
	s_cselect_b32 vcc_lo, s21, s24
	s_add_i32 m0, s77, 0xc000
	ds_read_b128 v[184:187], v161
	ds_read_b128 v[188:191], v161 offset:1024
	ds_read_b128 v[192:195], v161 offset:2048
	ds_read_b128 v[196:199], v161 offset:3072
	ds_read_b128 v[200:203], v161 offset:4096
	ds_read_b128 v[204:207], v161 offset:5120
	ds_read_b128 v[208:211], v161 offset:6144
	ds_read_b128 v[212:215], v161 offset:7168
	global_load_lds_dwordx4 v140, s[22:23]
	s_add_i32 m0, s77, 0xe000
	s_nop 0
	s_add_u32 s98, s22, s6
	s_addc_u32 s99, s23, s7
	global_load_lds_dwordx4 v140, s[98:99]
	s_waitcnt vmcnt(8)
	s_waitcnt lgkmcnt(0)
	s_barrier
	s_setprio 1
	s_waitcnt lgkmcnt(0)
	v_mfma_i32_16x16x64_i8 v[0:3], v[128:131], v[184:187], v[0:3]
	v_mfma_i32_16x16x64_i8 v[56:59], v[146:149], v[184:187], v[56:59]
	v_mfma_i32_16x16x64_i8 v[4:7], v[128:131], v[192:195], v[4:7]
	v_mfma_i32_16x16x64_i8 v[52:55], v[146:149], v[192:195], v[52:55]
	v_mfma_i32_16x16x64_i8 v[12:15], v[128:131], v[200:203], v[12:15]
	v_mfma_i32_16x16x64_i8 v[48:51], v[146:149], v[200:203], v[48:51]
	v_mfma_i32_16x16x64_i8 v[8:11], v[128:131], v[208:211], v[8:11]
	v_mfma_i32_16x16x64_i8 v[44:47], v[146:149], v[208:211], v[44:47]
	v_mfma_i32_16x16x64_i8 v[0:3], v[132:135], v[188:191], v[0:3]
	v_mfma_i32_16x16x64_i8 v[56:59], v[164:167], v[188:191], v[56:59]
	v_mfma_i32_16x16x64_i8 v[4:7], v[132:135], v[196:199], v[4:7]
	v_mfma_i32_16x16x64_i8 v[52:55], v[164:167], v[196:199], v[52:55]
	v_mfma_i32_16x16x64_i8 v[12:15], v[132:135], v[204:207], v[12:15]
	v_mfma_i32_16x16x64_i8 v[48:51], v[164:167], v[204:207], v[48:51]
	v_mfma_i32_16x16x64_i8 v[8:11], v[132:135], v[212:215], v[8:11]
	v_mfma_i32_16x16x64_i8 v[44:47], v[164:167], v[212:215], v[44:47]
	s_setprio 0
	s_setprio 1
	v_mfma_i32_16x16x64_i8 v[88:91], v[168:171], v[184:187], v[88:91]
	v_mfma_i32_16x16x64_i8 v[120:123], v[176:179], v[184:187], v[120:123]
	v_mfma_i32_16x16x64_i8 v[84:87], v[168:171], v[192:195], v[84:87]
	v_mfma_i32_16x16x64_i8 v[116:119], v[176:179], v[192:195], v[116:119]
	v_mfma_i32_16x16x64_i8 v[80:83], v[168:171], v[200:203], v[80:83]
	v_mfma_i32_16x16x64_i8 v[112:115], v[176:179], v[200:203], v[112:115]
	v_mfma_i32_16x16x64_i8 v[76:79], v[168:171], v[208:211], v[76:79]
	v_mfma_i32_16x16x64_i8 v[108:111], v[176:179], v[208:211], v[108:111]
	v_mfma_i32_16x16x64_i8 v[88:91], v[172:175], v[188:191], v[88:91]
	v_mfma_i32_16x16x64_i8 v[120:123], v[180:183], v[188:191], v[120:123]
	v_mfma_i32_16x16x64_i8 v[84:87], v[172:175], v[196:199], v[84:87]
	v_mfma_i32_16x16x64_i8 v[116:119], v[180:183], v[196:199], v[116:119]
	v_mfma_i32_16x16x64_i8 v[80:83], v[172:175], v[204:207], v[80:83]
	v_mfma_i32_16x16x64_i8 v[112:115], v[180:183], v[204:207], v[112:115]
	v_mfma_i32_16x16x64_i8 v[76:79], v[172:175], v[212:215], v[76:79]
	v_mfma_i32_16x16x64_i8 v[108:111], v[180:183], v[212:215], v[108:111]
	s_setprio 0
	s_barrier
	s_add_i32 s36, s86, s63
	s_mov_b32 m0, s36
	ds_read_b128 v[184:187], v161 offset:16384
	ds_read_b128 v[188:191], v161 offset:17408
	ds_read_b128 v[192:195], v161 offset:18432
	ds_read_b128 v[196:199], v161 offset:19456
	ds_read_b128 v[200:203], v161 offset:20480
	ds_read_b128 v[204:207], v161 offset:21504
	ds_read_b128 v[208:211], v161 offset:22528
	ds_read_b128 v[212:215], v161 offset:23552
	global_load_lds_dwordx4 v138, vcc
	s_add_i32 m0, s36, 0x2000
	s_add_i32 s36, s87, s63
	s_add_u32 s98, vcc_lo, s6
	s_addc_u32 s99, vcc_hi, s7
	global_load_lds_dwordx4 v138, s[98:99]
	s_mov_b32 m0, s36
	s_nop 0
	s_add_u32 s98, vcc_lo, s8
	s_addc_u32 s99, vcc_hi, s9
	global_load_lds_dwordx4 v138, s[98:99]
	s_add_i32 m0, s36, 0x2000
	s_nop 0
	s_add_u32 s98, vcc_lo, s10
	s_addc_u32 s99, vcc_hi, s11
	global_load_lds_dwordx4 v138, s[98:99]
	s_mov_b32 m0, s77
	s_nop 0
	global_load_lds_dwordx4 v136, s[80:81]
	s_mov_b32 m0, s97
	s_nop 0
	s_add_u32 s98, s80, s6
	s_addc_u32 s99, s81, s7
	global_load_lds_dwordx4 v136, s[98:99]
	s_waitcnt vmcnt(8)
	s_waitcnt lgkmcnt(0)
	s_barrier
	s_setprio 1
	s_waitcnt lgkmcnt(0)
	v_mfma_i32_16x16x64_i8 v[20:23], v[128:131], v[184:187], v[20:23]
	v_mfma_i32_16x16x64_i8 v[40:43], v[146:149], v[184:187], v[40:43]
	v_mfma_i32_16x16x64_i8 v[16:19], v[128:131], v[192:195], v[16:19]
	v_mfma_i32_16x16x64_i8 v[36:39], v[146:149], v[192:195], v[36:39]
	v_mfma_i32_16x16x64_i8 v[24:27], v[128:131], v[200:203], v[24:27]
	v_mfma_i32_16x16x64_i8 v[32:35], v[146:149], v[200:203], v[32:35]
	v_mfma_i32_16x16x64_i8 v[28:31], v[128:131], v[208:211], v[28:31]
	v_mfma_i32_16x16x64_i8 v[60:63], v[146:149], v[208:211], v[60:63]
	v_mfma_i32_16x16x64_i8 v[20:23], v[132:135], v[188:191], v[20:23]
	v_mfma_i32_16x16x64_i8 v[40:43], v[164:167], v[188:191], v[40:43]
	v_mfma_i32_16x16x64_i8 v[16:19], v[132:135], v[196:199], v[16:19]
	v_mfma_i32_16x16x64_i8 v[36:39], v[164:167], v[196:199], v[36:39]
	v_mfma_i32_16x16x64_i8 v[24:27], v[132:135], v[204:207], v[24:27]
	v_mfma_i32_16x16x64_i8 v[32:35], v[164:167], v[204:207], v[32:35]
	v_mfma_i32_16x16x64_i8 v[28:31], v[132:135], v[212:215], v[28:31]
	v_mfma_i32_16x16x64_i8 v[60:63], v[164:167], v[212:215], v[60:63]
	s_setprio 0
	s_setprio 1
	v_mfma_i32_16x16x64_i8 v[72:75], v[168:171], v[184:187], v[72:75]
	v_mfma_i32_16x16x64_i8 v[104:107], v[176:179], v[184:187], v[104:107]
	v_mfma_i32_16x16x64_i8 v[68:71], v[168:171], v[192:195], v[68:71]
	v_mfma_i32_16x16x64_i8 v[100:103], v[176:179], v[192:195], v[100:103]
	v_mfma_i32_16x16x64_i8 v[64:67], v[168:171], v[200:203], v[64:67]
	v_mfma_i32_16x16x64_i8 v[96:99], v[176:179], v[200:203], v[96:99]
	v_mfma_i32_16x16x64_i8 v[92:95], v[168:171], v[208:211], v[92:95]
	v_mfma_i32_16x16x64_i8 v[124:127], v[176:179], v[208:211], v[124:127]
	v_mfma_i32_16x16x64_i8 v[72:75], v[172:175], v[188:191], v[72:75]
	v_mfma_i32_16x16x64_i8 v[104:107], v[180:183], v[188:191], v[104:107]
	v_mfma_i32_16x16x64_i8 v[68:71], v[172:175], v[196:199], v[68:71]
	v_mfma_i32_16x16x64_i8 v[100:103], v[180:183], v[196:199], v[100:103]
	v_mfma_i32_16x16x64_i8 v[64:67], v[172:175], v[204:207], v[64:67]
	v_mfma_i32_16x16x64_i8 v[96:99], v[180:183], v[204:207], v[96:99]
	v_mfma_i32_16x16x64_i8 v[92:95], v[172:175], v[212:215], v[92:95]
	v_mfma_i32_16x16x64_i8 v[124:127], v[180:183], v[212:215], v[124:127]
	s_setprio 0
	s_barrier
	s_add_i32 s36, 0, 0x18000
	v_add_u32_e32 v152, s36, v153
	s_add_i32 s37, 0, 0x1c000
	ds_read_b128 v[128:131], v152
	ds_read_b128 v[132:135], v152 offset:1024
	ds_read_b128 v[146:149], v152 offset:2048
	ds_read_b128 v[164:167], v152 offset:3072
	v_add_u32_e32 v152, s37, v153
	ds_read_b128 v[168:171], v152
	ds_read_b128 v[172:175], v152 offset:1024
	ds_read_b128 v[176:179], v152 offset:2048
	ds_read_b128 v[180:183], v152 offset:3072
	s_mov_b32 m0, s33
	ds_read_b128 v[184:187], v161 offset:32768
	ds_read_b128 v[188:191], v161 offset:33792
	ds_read_b128 v[192:195], v161 offset:34816
	ds_read_b128 v[196:199], v161 offset:35840
	ds_read_b128 v[200:203], v161 offset:36864
	ds_read_b128 v[204:207], v161 offset:37888
	ds_read_b128 v[208:211], v161 offset:38912
	ds_read_b128 v[212:215], v161 offset:39936
	s_add_u32 s98, s80, s8
	s_addc_u32 s99, s81, s9
	global_load_lds_dwordx4 v136, s[98:99]
	s_mov_b32 m0, s93
	s_nop 0
	s_add_u32 s98, s80, s10
	s_addc_u32 s99, s81, s11
	global_load_lds_dwordx4 v136, s[98:99]
	s_waitcnt vmcnt(8)
	s_waitcnt lgkmcnt(0)
	s_barrier
	s_setprio 1
	s_waitcnt lgkmcnt(0)
	v_mfma_i32_16x16x64_i8 v[0:3], v[128:131], v[184:187], v[0:3]
	v_mfma_i32_16x16x64_i8 v[56:59], v[146:149], v[184:187], v[56:59]
	v_mfma_i32_16x16x64_i8 v[4:7], v[128:131], v[192:195], v[4:7]
	v_mfma_i32_16x16x64_i8 v[52:55], v[146:149], v[192:195], v[52:55]
	v_mfma_i32_16x16x64_i8 v[12:15], v[128:131], v[200:203], v[12:15]
	v_mfma_i32_16x16x64_i8 v[48:51], v[146:149], v[200:203], v[48:51]
	v_mfma_i32_16x16x64_i8 v[8:11], v[128:131], v[208:211], v[8:11]
	v_mfma_i32_16x16x64_i8 v[44:47], v[146:149], v[208:211], v[44:47]
	v_mfma_i32_16x16x64_i8 v[0:3], v[132:135], v[188:191], v[0:3]
	v_mfma_i32_16x16x64_i8 v[56:59], v[164:167], v[188:191], v[56:59]
	v_mfma_i32_16x16x64_i8 v[4:7], v[132:135], v[196:199], v[4:7]
	v_mfma_i32_16x16x64_i8 v[52:55], v[164:167], v[196:199], v[52:55]
	v_mfma_i32_16x16x64_i8 v[12:15], v[132:135], v[204:207], v[12:15]
	v_mfma_i32_16x16x64_i8 v[48:51], v[164:167], v[204:207], v[48:51]
	v_mfma_i32_16x16x64_i8 v[8:11], v[132:135], v[212:215], v[8:11]
	v_mfma_i32_16x16x64_i8 v[44:47], v[164:167], v[212:215], v[44:47]
	s_setprio 0
	s_setprio 1
	v_mfma_i32_16x16x64_i8 v[88:91], v[168:171], v[184:187], v[88:91]
	v_mfma_i32_16x16x64_i8 v[120:123], v[176:179], v[184:187], v[120:123]
	v_mfma_i32_16x16x64_i8 v[84:87], v[168:171], v[192:195], v[84:87]
	v_mfma_i32_16x16x64_i8 v[116:119], v[176:179], v[192:195], v[116:119]
	v_mfma_i32_16x16x64_i8 v[80:83], v[168:171], v[200:203], v[80:83]
	v_mfma_i32_16x16x64_i8 v[112:115], v[176:179], v[200:203], v[112:115]
	v_mfma_i32_16x16x64_i8 v[76:79], v[168:171], v[208:211], v[76:79]
	v_mfma_i32_16x16x64_i8 v[108:111], v[176:179], v[208:211], v[108:111]
	v_mfma_i32_16x16x64_i8 v[88:91], v[172:175], v[188:191], v[88:91]
	v_mfma_i32_16x16x64_i8 v[120:123], v[180:183], v[188:191], v[120:123]
	v_mfma_i32_16x16x64_i8 v[84:87], v[172:175], v[196:199], v[84:87]
	v_mfma_i32_16x16x64_i8 v[116:119], v[180:183], v[196:199], v[116:119]
	v_mfma_i32_16x16x64_i8 v[80:83], v[172:175], v[204:207], v[80:83]
	v_mfma_i32_16x16x64_i8 v[112:115], v[180:183], v[204:207], v[112:115]
	v_mfma_i32_16x16x64_i8 v[76:79], v[172:175], v[212:215], v[76:79]
	v_mfma_i32_16x16x64_i8 v[108:111], v[180:183], v[212:215], v[108:111]
	s_setprio 0
	s_barrier
	s_add_i32 s36, s36, s63
	s_mov_b32 m0, s36
	ds_read_b128 v[184:187], v161 offset:49152
	ds_read_b128 v[188:191], v161 offset:50176
	ds_read_b128 v[192:195], v161 offset:51200
	ds_read_b128 v[196:199], v161 offset:52224
	ds_read_b128 v[200:203], v161 offset:53248
	ds_read_b128 v[204:207], v161 offset:54272
	ds_read_b128 v[208:211], v161 offset:55296
	ds_read_b128 v[212:215], v161 offset:56320
	s_add_u32 s98, vcc_lo, s46
	s_addc_u32 s99, vcc_hi, s47
	global_load_lds_dwordx4 v138, s[98:99]
	s_add_i32 m0, s36, 0x2000
	s_add_i32 s36, s37, s63
	s_add_u32 s98, vcc_lo, s48
	s_addc_u32 s99, vcc_hi, s49
	global_load_lds_dwordx4 v138, s[98:99]
	s_mov_b32 m0, s36
	s_add_u32 s98, vcc_lo, s54
	s_addc_u32 s99, vcc_hi, s55
	global_load_lds_dwordx4 v138, s[98:99]
	s_add_i32 m0, s36, 0x2000
	s_nop 0
	s_add_u32 s98, vcc_lo, s56
	s_addc_u32 s99, vcc_hi, s57
	global_load_lds_dwordx4 v138, s[98:99]
	s_mov_b32 m0, s95
	s_nop 0
	s_add_u32 s98, s80, s46
	s_addc_u32 s99, s81, s47
	global_load_lds_dwordx4 v136, s[98:99]
	s_mov_b32 m0, s82
	s_nop 0
	s_add_u32 s98, s80, s48
	s_addc_u32 s99, s81, s49
	global_load_lds_dwordx4 v136, s[98:99]
	s_waitcnt vmcnt(8)
	s_waitcnt lgkmcnt(0)
	s_barrier
	s_setprio 1
	s_waitcnt lgkmcnt(0)
	v_mfma_i32_16x16x64_i8 v[20:23], v[128:131], v[184:187], v[20:23]
	v_mfma_i32_16x16x64_i8 v[40:43], v[146:149], v[184:187], v[40:43]
	v_mfma_i32_16x16x64_i8 v[16:19], v[128:131], v[192:195], v[16:19]
	v_mfma_i32_16x16x64_i8 v[36:39], v[146:149], v[192:195], v[36:39]
	v_mfma_i32_16x16x64_i8 v[24:27], v[128:131], v[200:203], v[24:27]
	v_mfma_i32_16x16x64_i8 v[32:35], v[146:149], v[200:203], v[32:35]
	v_mfma_i32_16x16x64_i8 v[28:31], v[128:131], v[208:211], v[28:31]
	v_mfma_i32_16x16x64_i8 v[60:63], v[146:149], v[208:211], v[60:63]
	v_mfma_i32_16x16x64_i8 v[20:23], v[132:135], v[188:191], v[20:23]
	v_mfma_i32_16x16x64_i8 v[40:43], v[164:167], v[188:191], v[40:43]
	v_mfma_i32_16x16x64_i8 v[16:19], v[132:135], v[196:199], v[16:19]
	v_mfma_i32_16x16x64_i8 v[36:39], v[164:167], v[196:199], v[36:39]
	v_mfma_i32_16x16x64_i8 v[24:27], v[132:135], v[204:207], v[24:27]
	v_mfma_i32_16x16x64_i8 v[32:35], v[164:167], v[204:207], v[32:35]
	v_mfma_i32_16x16x64_i8 v[28:31], v[132:135], v[212:215], v[28:31]
	v_mfma_i32_16x16x64_i8 v[60:63], v[164:167], v[212:215], v[60:63]
	s_setprio 0
	s_setprio 1
	v_mfma_i32_16x16x64_i8 v[72:75], v[168:171], v[184:187], v[72:75]
	v_mfma_i32_16x16x64_i8 v[104:107], v[176:179], v[184:187], v[104:107]
	v_mfma_i32_16x16x64_i8 v[68:71], v[168:171], v[192:195], v[68:71]
	v_mfma_i32_16x16x64_i8 v[100:103], v[176:179], v[192:195], v[100:103]
	v_mfma_i32_16x16x64_i8 v[64:67], v[168:171], v[200:203], v[64:67]
	v_mfma_i32_16x16x64_i8 v[96:99], v[176:179], v[200:203], v[96:99]
	v_mfma_i32_16x16x64_i8 v[92:95], v[168:171], v[208:211], v[92:95]
	v_mfma_i32_16x16x64_i8 v[124:127], v[176:179], v[208:211], v[124:127]
	v_mfma_i32_16x16x64_i8 v[72:75], v[172:175], v[188:191], v[72:75]
	v_mfma_i32_16x16x64_i8 v[104:107], v[180:183], v[188:191], v[104:107]
	v_mfma_i32_16x16x64_i8 v[68:71], v[172:175], v[196:199], v[68:71]
	v_mfma_i32_16x16x64_i8 v[100:103], v[180:183], v[196:199], v[100:103]
	v_mfma_i32_16x16x64_i8 v[64:67], v[172:175], v[204:207], v[64:67]
	v_mfma_i32_16x16x64_i8 v[96:99], v[180:183], v[204:207], v[96:99]
	v_mfma_i32_16x16x64_i8 v[92:95], v[172:175], v[212:215], v[92:95]
	v_mfma_i32_16x16x64_i8 v[124:127], v[180:183], v[212:215], v[124:127]
	s_setprio 0
	s_barrier
	s_add_i32 s78, s78, 2
	s_add_u32 s24, s24, 0x100
	s_addc_u32 s45, s45, 0
	s_add_u32 s22, s22, 0x100
	s_addc_u32 s23, s23, 0
	s_cmp_gt_u32 s78, 29
	s_cbranch_scc0 .LBB0_225
	v_readlane_b32 s14, v250, 9
	v_readlane_b32 s15, v250, 10
	s_and_b64 vcc, exec, s[14:15]
	s_cbranch_vccz .LBB0_228
	s_barrier

.LBB0_298:
	ds_read_b128 v[128:131], v153
	ds_read_b128 v[132:135], v153 offset:1024
	ds_read_b128 v[146:149], v153 offset:2048
	ds_read_b128 v[158:161], v153 offset:3072
	ds_read_b128 v[162:165], v154
	ds_read_b128 v[166:169], v154 offset:1024
	ds_read_b128 v[170:173], v154 offset:2048
	ds_read_b128 v[174:177], v154 offset:3072
	s_add_u32 s36, s78, 0xfff00080
	s_addc_u32 s37, s79, -1
	s_cmp_eq_u32 s81, 60
	s_cselect_b32 s97, s5, s37
	s_cselect_b32 s96, s14, s36
	s_cselect_b32 vcc_hi, s20, s80
	s_cselect_b32 vcc_lo, s21, s22
	s_add_i32 m0, s33, 0xc000
	ds_read_b128 v[178:181], v155
	ds_read_b128 v[182:185], v155 offset:1024
	ds_read_b128 v[186:189], v155 offset:2048
	ds_read_b128 v[190:193], v155 offset:3072
	ds_read_b128 v[194:197], v155 offset:4096
	ds_read_b128 v[198:201], v155 offset:5120
	ds_read_b128 v[202:205], v155 offset:6144
	ds_read_b128 v[206:209], v155 offset:7168
	global_load_lds_dwordx4 v140, s[78:79]
	s_add_i32 m0, s33, 0xe000
	s_nop 0
	s_add_u32 s98, s78, s0
	s_addc_u32 s99, s79, s1
	global_load_lds_dwordx4 v140, s[98:99]
	s_waitcnt vmcnt(8)
	s_waitcnt lgkmcnt(0)
	s_barrier
	s_setprio 1
	s_waitcnt lgkmcnt(0)
	v_mfma_f32_16x16x32_bf16 v[124:127], v[128:131], v[178:181], v[124:127]
	v_mfma_f32_16x16x32_bf16 v[120:123], v[146:149], v[178:181], v[120:123]
	v_mfma_f32_16x16x32_bf16 v[112:115], v[128:131], v[186:189], v[112:115]
	v_mfma_f32_16x16x32_bf16 v[108:111], v[146:149], v[186:189], v[108:111]
	v_mfma_f32_16x16x32_bf16 v[100:103], v[128:131], v[194:197], v[100:103]
	v_mfma_f32_16x16x32_bf16 v[92:95], v[146:149], v[194:197], v[92:95]
	v_mfma_f32_16x16x32_bf16 v[84:87], v[128:131], v[202:205], v[84:87]
	v_mfma_f32_16x16x32_bf16 v[76:79], v[146:149], v[202:205], v[76:79]
	v_mfma_f32_16x16x32_bf16 v[124:127], v[132:135], v[182:185], v[124:127]
	v_mfma_f32_16x16x32_bf16 v[120:123], v[158:161], v[182:185], v[120:123]
	v_mfma_f32_16x16x32_bf16 v[112:115], v[132:135], v[190:193], v[112:115]
	v_mfma_f32_16x16x32_bf16 v[108:111], v[158:161], v[190:193], v[108:111]
	v_mfma_f32_16x16x32_bf16 v[100:103], v[132:135], v[198:201], v[100:103]
	v_mfma_f32_16x16x32_bf16 v[92:95], v[158:161], v[198:201], v[92:95]
	v_mfma_f32_16x16x32_bf16 v[84:87], v[132:135], v[206:209], v[84:87]
	v_mfma_f32_16x16x32_bf16 v[76:79], v[158:161], v[206:209], v[76:79]
	s_setprio 0
	s_setprio 1
	v_mfma_f32_16x16x32_bf16 v[116:119], v[162:165], v[178:181], v[116:119]
	v_mfma_f32_16x16x32_bf16 v[104:107], v[170:173], v[178:181], v[104:107]
	v_mfma_f32_16x16x32_bf16 v[96:99], v[162:165], v[186:189], v[96:99]
	v_mfma_f32_16x16x32_bf16 v[88:91], v[170:173], v[186:189], v[88:91]
	v_mfma_f32_16x16x32_bf16 v[80:83], v[162:165], v[194:197], v[80:83]
	v_mfma_f32_16x16x32_bf16 v[72:75], v[170:173], v[194:197], v[72:75]
	v_mfma_f32_16x16x32_bf16 v[68:71], v[162:165], v[202:205], v[68:71]
	v_mfma_f32_16x16x32_bf16 v[64:67], v[170:173], v[202:205], v[64:67]
	v_mfma_f32_16x16x32_bf16 v[116:119], v[166:169], v[182:185], v[116:119]
	v_mfma_f32_16x16x32_bf16 v[104:107], v[174:177], v[182:185], v[104:107]
	v_mfma_f32_16x16x32_bf16 v[96:99], v[166:169], v[190:193], v[96:99]
	v_mfma_f32_16x16x32_bf16 v[88:91], v[174:177], v[190:193], v[88:91]
	v_mfma_f32_16x16x32_bf16 v[80:83], v[166:169], v[198:201], v[80:83]
	v_mfma_f32_16x16x32_bf16 v[72:75], v[174:177], v[198:201], v[72:75]
	v_mfma_f32_16x16x32_bf16 v[68:71], v[166:169], v[206:209], v[68:71]
	v_mfma_f32_16x16x32_bf16 v[64:67], v[174:177], v[206:209], v[64:67]
	s_setprio 0
	s_barrier
	s_add_i32 s36, s82, s63
	s_mov_b32 m0, s36
	ds_read_b128 v[178:181], v155 offset:16384
	ds_read_b128 v[182:185], v155 offset:17408
	ds_read_b128 v[186:189], v155 offset:18432
	ds_read_b128 v[190:193], v155 offset:19456
	ds_read_b128 v[194:197], v155 offset:20480
	ds_read_b128 v[198:201], v155 offset:21504
	ds_read_b128 v[202:205], v155 offset:22528
	ds_read_b128 v[206:209], v155 offset:23552
	global_load_lds_dwordx4 v138, vcc
	s_add_i32 m0, s36, 0x2000
	s_add_i32 s36, s83, s63
	s_add_u32 s98, vcc_lo, s0
	s_addc_u32 s99, vcc_hi, s1
	global_load_lds_dwordx4 v138, s[98:99]
	s_mov_b32 m0, s36
	s_nop 0
	s_add_u32 s98, vcc_lo, s6
	s_addc_u32 s99, vcc_hi, s7
	global_load_lds_dwordx4 v138, s[98:99]
	s_add_i32 m0, s36, 0x2000
	s_nop 0
	s_add_u32 s98, vcc_lo, s8
	s_addc_u32 s99, vcc_hi, s9
	global_load_lds_dwordx4 v138, s[98:99]
	s_mov_b32 m0, s33
	s_nop 0
	global_load_lds_dwordx4 v136, s[96:97]
	s_mov_b32 m0, s55
	s_nop 0
	s_add_u32 s98, s96, s0
	s_addc_u32 s99, s97, s1
	global_load_lds_dwordx4 v136, s[98:99]
	s_waitcnt vmcnt(8)
	s_waitcnt lgkmcnt(0)
	s_barrier
	s_setprio 1
	s_waitcnt lgkmcnt(0)
	v_mfma_f32_16x16x32_bf16 v[60:63], v[128:131], v[178:181], v[60:63]
	v_mfma_f32_16x16x32_bf16 v[56:59], v[146:149], v[178:181], v[56:59]
	v_mfma_f32_16x16x32_bf16 v[52:55], v[128:131], v[186:189], v[52:55]
	v_mfma_f32_16x16x32_bf16 v[44:47], v[146:149], v[186:189], v[44:47]
	v_mfma_f32_16x16x32_bf16 v[36:39], v[128:131], v[194:197], v[36:39]
	v_mfma_f32_16x16x32_bf16 v[28:31], v[146:149], v[194:197], v[28:31]
	v_mfma_f32_16x16x32_bf16 v[20:23], v[128:131], v[202:205], v[20:23]
	v_mfma_f32_16x16x32_bf16 v[12:15], v[146:149], v[202:205], v[12:15]
	v_mfma_f32_16x16x32_bf16 v[60:63], v[132:135], v[182:185], v[60:63]
	v_mfma_f32_16x16x32_bf16 v[56:59], v[158:161], v[182:185], v[56:59]
	v_mfma_f32_16x16x32_bf16 v[52:55], v[132:135], v[190:193], v[52:55]
	v_mfma_f32_16x16x32_bf16 v[44:47], v[158:161], v[190:193], v[44:47]
	v_mfma_f32_16x16x32_bf16 v[36:39], v[132:135], v[198:201], v[36:39]
	v_mfma_f32_16x16x32_bf16 v[28:31], v[158:161], v[198:201], v[28:31]
	v_mfma_f32_16x16x32_bf16 v[20:23], v[132:135], v[206:209], v[20:23]
	v_mfma_f32_16x16x32_bf16 v[12:15], v[158:161], v[206:209], v[12:15]
	s_setprio 0
	s_setprio 1
	v_mfma_f32_16x16x32_bf16 v[48:51], v[162:165], v[178:181], v[48:51]
	v_mfma_f32_16x16x32_bf16 v[40:43], v[170:173], v[178:181], v[40:43]
	v_mfma_f32_16x16x32_bf16 v[32:35], v[162:165], v[186:189], v[32:35]
	v_mfma_f32_16x16x32_bf16 v[24:27], v[170:173], v[186:189], v[24:27]
	v_mfma_f32_16x16x32_bf16 v[16:19], v[162:165], v[194:197], v[16:19]
	v_mfma_f32_16x16x32_bf16 v[8:11], v[170:173], v[194:197], v[8:11]
	v_mfma_f32_16x16x32_bf16 v[4:7], v[162:165], v[202:205], v[4:7]
	v_mfma_f32_16x16x32_bf16 v[0:3], v[170:173], v[202:205], v[0:3]
	v_mfma_f32_16x16x32_bf16 v[48:51], v[166:169], v[182:185], v[48:51]
	v_mfma_f32_16x16x32_bf16 v[40:43], v[174:177], v[182:185], v[40:43]
	v_mfma_f32_16x16x32_bf16 v[32:35], v[166:169], v[190:193], v[32:35]
	v_mfma_f32_16x16x32_bf16 v[24:27], v[174:177], v[190:193], v[24:27]
	v_mfma_f32_16x16x32_bf16 v[16:19], v[166:169], v[198:201], v[16:19]
	v_mfma_f32_16x16x32_bf16 v[8:11], v[174:177], v[198:201], v[8:11]
	v_mfma_f32_16x16x32_bf16 v[4:7], v[166:169], v[206:209], v[4:7]
	v_mfma_f32_16x16x32_bf16 v[0:3], v[174:177], v[206:209], v[0:3]
	s_setprio 0
	s_barrier
	s_add_i32 s36, 0, 0x18000
	v_add_u32_e32 v157, s36, v152
	s_add_i32 s37, 0, 0x1c000
	ds_read_b128 v[128:131], v157
	ds_read_b128 v[132:135], v157 offset:1024
	ds_read_b128 v[146:149], v157 offset:2048
	ds_read_b128 v[158:161], v157 offset:3072
	v_add_u32_e32 v157, s37, v152
	ds_read_b128 v[162:165], v157
	ds_read_b128 v[166:169], v157 offset:1024
	ds_read_b128 v[170:173], v157 offset:2048
	ds_read_b128 v[174:177], v157 offset:3072
	s_mov_b32 m0, s57
	ds_read_b128 v[178:181], v155 offset:32768
	ds_read_b128 v[182:185], v155 offset:33792
	ds_read_b128 v[186:189], v155 offset:34816
	ds_read_b128 v[190:193], v155 offset:35840
	ds_read_b128 v[194:197], v155 offset:36864
	ds_read_b128 v[198:201], v155 offset:37888
	ds_read_b128 v[202:205], v155 offset:38912
	ds_read_b128 v[206:209], v155 offset:39936
	s_add_u32 s98, s96, s6
	s_addc_u32 s99, s97, s7
	global_load_lds_dwordx4 v136, s[98:99]
	s_mov_b32 m0, s59
	s_nop 0
	s_add_u32 s98, s96, s8
	s_addc_u32 s99, s97, s9
	global_load_lds_dwordx4 v136, s[98:99]
	s_waitcnt vmcnt(8)
	s_waitcnt lgkmcnt(0)
	s_barrier
	s_setprio 1
	s_waitcnt lgkmcnt(0)
	v_mfma_f32_16x16x32_bf16 v[124:127], v[128:131], v[178:181], v[124:127]
	v_mfma_f32_16x16x32_bf16 v[120:123], v[146:149], v[178:181], v[120:123]
	v_mfma_f32_16x16x32_bf16 v[112:115], v[128:131], v[186:189], v[112:115]
	v_mfma_f32_16x16x32_bf16 v[108:111], v[146:149], v[186:189], v[108:111]
	v_mfma_f32_16x16x32_bf16 v[100:103], v[128:131], v[194:197], v[100:103]
	v_mfma_f32_16x16x32_bf16 v[92:95], v[146:149], v[194:197], v[92:95]
	v_mfma_f32_16x16x32_bf16 v[84:87], v[128:131], v[202:205], v[84:87]
	v_mfma_f32_16x16x32_bf16 v[76:79], v[146:149], v[202:205], v[76:79]
	v_mfma_f32_16x16x32_bf16 v[124:127], v[132:135], v[182:185], v[124:127]
	v_mfma_f32_16x16x32_bf16 v[120:123], v[158:161], v[182:185], v[120:123]
	v_mfma_f32_16x16x32_bf16 v[112:115], v[132:135], v[190:193], v[112:115]
	v_mfma_f32_16x16x32_bf16 v[108:111], v[158:161], v[190:193], v[108:111]
	v_mfma_f32_16x16x32_bf16 v[100:103], v[132:135], v[198:201], v[100:103]
	v_mfma_f32_16x16x32_bf16 v[92:95], v[158:161], v[198:201], v[92:95]
	v_mfma_f32_16x16x32_bf16 v[84:87], v[132:135], v[206:209], v[84:87]
	v_mfma_f32_16x16x32_bf16 v[76:79], v[158:161], v[206:209], v[76:79]
	s_setprio 0
	s_setprio 1
	v_mfma_f32_16x16x32_bf16 v[116:119], v[162:165], v[178:181], v[116:119]
	v_mfma_f32_16x16x32_bf16 v[104:107], v[170:173], v[178:181], v[104:107]
	v_mfma_f32_16x16x32_bf16 v[96:99], v[162:165], v[186:189], v[96:99]
	v_mfma_f32_16x16x32_bf16 v[88:91], v[170:173], v[186:189], v[88:91]
	v_mfma_f32_16x16x32_bf16 v[80:83], v[162:165], v[194:197], v[80:83]
	v_mfma_f32_16x16x32_bf16 v[72:75], v[170:173], v[194:197], v[72:75]
	v_mfma_f32_16x16x32_bf16 v[68:71], v[162:165], v[202:205], v[68:71]
	v_mfma_f32_16x16x32_bf16 v[64:67], v[170:173], v[202:205], v[64:67]
	v_mfma_f32_16x16x32_bf16 v[116:119], v[166:169], v[182:185], v[116:119]
	v_mfma_f32_16x16x32_bf16 v[104:107], v[174:177], v[182:185], v[104:107]
	v_mfma_f32_16x16x32_bf16 v[96:99], v[166:169], v[190:193], v[96:99]
	v_mfma_f32_16x16x32_bf16 v[88:91], v[174:177], v[190:193], v[88:91]
	v_mfma_f32_16x16x32_bf16 v[80:83], v[166:169], v[198:201], v[80:83]
	v_mfma_f32_16x16x32_bf16 v[72:75], v[174:177], v[198:201], v[72:75]
	v_mfma_f32_16x16x32_bf16 v[68:71], v[166:169], v[206:209], v[68:71]
	v_mfma_f32_16x16x32_bf16 v[64:67], v[174:177], v[206:209], v[64:67]
	s_setprio 0
	s_barrier
	s_add_i32 s36, s36, s63
	s_mov_b32 m0, s36
	ds_read_b128 v[178:181], v155 offset:49152
	ds_read_b128 v[182:185], v155 offset:50176
	ds_read_b128 v[186:189], v155 offset:51200
	ds_read_b128 v[190:193], v155 offset:52224
	ds_read_b128 v[194:197], v155 offset:53248
	ds_read_b128 v[198:201], v155 offset:54272
	ds_read_b128 v[202:205], v155 offset:55296
	ds_read_b128 v[206:209], v155 offset:56320
	s_add_u32 s98, vcc_lo, s24
	s_addc_u32 s99, vcc_hi, s25
	global_load_lds_dwordx4 v138, s[98:99]
	s_add_i32 m0, s36, 0x2000
	s_add_i32 s36, s37, s63
	s_add_u32 s98, vcc_lo, s34
	s_addc_u32 s99, vcc_hi, s35
	global_load_lds_dwordx4 v138, s[98:99]
	s_mov_b32 m0, s36
	s_add_u32 s98, vcc_lo, s12
	s_addc_u32 s99, vcc_hi, s13
	global_load_lds_dwordx4 v138, s[98:99]
	s_add_i32 m0, s36, 0x2000
	s_nop 0
	s_add_u32 s98, vcc_lo, s18
	s_addc_u32 s99, vcc_hi, s19
	global_load_lds_dwordx4 v138, s[98:99]
	s_mov_b32 m0, s68
	s_nop 0
	s_add_u32 s98, s96, s24
	s_addc_u32 s99, s97, s25
	global_load_lds_dwordx4 v136, s[98:99]
	s_mov_b32 m0, s69
	s_nop 0
	s_add_u32 s98, s96, s34
	s_addc_u32 s99, s97, s35
	global_load_lds_dwordx4 v136, s[98:99]
	s_waitcnt vmcnt(8)
	s_waitcnt lgkmcnt(0)
	s_barrier
	s_setprio 1
	s_waitcnt lgkmcnt(0)
	v_mfma_f32_16x16x32_bf16 v[60:63], v[128:131], v[178:181], v[60:63]
	v_mfma_f32_16x16x32_bf16 v[56:59], v[146:149], v[178:181], v[56:59]
	v_mfma_f32_16x16x32_bf16 v[52:55], v[128:131], v[186:189], v[52:55]
	v_mfma_f32_16x16x32_bf16 v[44:47], v[146:149], v[186:189], v[44:47]
	v_mfma_f32_16x16x32_bf16 v[36:39], v[128:131], v[194:197], v[36:39]
	v_mfma_f32_16x16x32_bf16 v[28:31], v[146:149], v[194:197], v[28:31]
	v_mfma_f32_16x16x32_bf16 v[20:23], v[128:131], v[202:205], v[20:23]
	v_mfma_f32_16x16x32_bf16 v[12:15], v[146:149], v[202:205], v[12:15]
	v_mfma_f32_16x16x32_bf16 v[60:63], v[132:135], v[182:185], v[60:63]
	v_mfma_f32_16x16x32_bf16 v[56:59], v[158:161], v[182:185], v[56:59]
	v_mfma_f32_16x16x32_bf16 v[52:55], v[132:135], v[190:193], v[52:55]
	v_mfma_f32_16x16x32_bf16 v[44:47], v[158:161], v[190:193], v[44:47]
	v_mfma_f32_16x16x32_bf16 v[36:39], v[132:135], v[198:201], v[36:39]
	v_mfma_f32_16x16x32_bf16 v[28:31], v[158:161], v[198:201], v[28:31]
	v_mfma_f32_16x16x32_bf16 v[20:23], v[132:135], v[206:209], v[20:23]
	v_mfma_f32_16x16x32_bf16 v[12:15], v[158:161], v[206:209], v[12:15]
	s_setprio 0
	s_setprio 1
	v_mfma_f32_16x16x32_bf16 v[48:51], v[162:165], v[178:181], v[48:51]
	v_mfma_f32_16x16x32_bf16 v[40:43], v[170:173], v[178:181], v[40:43]
	v_mfma_f32_16x16x32_bf16 v[32:35], v[162:165], v[186:189], v[32:35]
	v_mfma_f32_16x16x32_bf16 v[24:27], v[170:173], v[186:189], v[24:27]
	v_mfma_f32_16x16x32_bf16 v[16:19], v[162:165], v[194:197], v[16:19]
	v_mfma_f32_16x16x32_bf16 v[8:11], v[170:173], v[194:197], v[8:11]
	v_mfma_f32_16x16x32_bf16 v[4:7], v[162:165], v[202:205], v[4:7]
	v_mfma_f32_16x16x32_bf16 v[0:3], v[170:173], v[202:205], v[0:3]
	v_mfma_f32_16x16x32_bf16 v[48:51], v[166:169], v[182:185], v[48:51]
	v_mfma_f32_16x16x32_bf16 v[40:43], v[174:177], v[182:185], v[40:43]
	v_mfma_f32_16x16x32_bf16 v[32:35], v[166:169], v[190:193], v[32:35]
	v_mfma_f32_16x16x32_bf16 v[24:27], v[174:177], v[190:193], v[24:27]
	v_mfma_f32_16x16x32_bf16 v[16:19], v[166:169], v[198:201], v[16:19]
	v_mfma_f32_16x16x32_bf16 v[8:11], v[174:177], v[198:201], v[8:11]
	v_mfma_f32_16x16x32_bf16 v[4:7], v[166:169], v[206:209], v[4:7]
	v_mfma_f32_16x16x32_bf16 v[0:3], v[174:177], v[206:209], v[0:3]
	s_setprio 0
	s_barrier
	s_add_i32 s81, s81, 2
	s_add_u32 s22, s22, 0x100
	s_addc_u32 s80, s80, 0
	s_add_u32 s78, s78, 0x100
	s_addc_u32 s79, s79, 0
	s_cmp_gt_u32 s81, 61
	s_cbranch_scc0 .LBB0_298
	s_and_b64 vcc, exec, s[26:27]
	s_cbranch_vccz .LBB0_301
	s_barrier

.LBB0_627:
	ds_read_b128 v[128:131], v151
	ds_read_b128 v[142:145], v151 offset:1024
	ds_read_b128 v[146:149], v151 offset:2048
	ds_read_b128 v[154:157], v151 offset:3072
	ds_read_b128 v[158:161], v152
	ds_read_b128 v[162:165], v152 offset:1024
	ds_read_b128 v[166:169], v152 offset:2048
	ds_read_b128 v[170:173], v152 offset:3072
	s_add_u32 s50, s60, 0xfff00080
	s_addc_u32 s51, s61, -1
	s_cmp_eq_u32 s62, 60
	s_cselect_b32 s77, s5, s51
	s_cselect_b32 s76, s49, s50
	s_cselect_b32 s79, s47, s75
	s_cselect_b32 s78, s59, s74
	s_add_i32 m0, s20, 0xc000
	ds_read_b128 v[174:177], v153
	ds_read_b128 v[178:181], v153 offset:1024
	ds_read_b128 v[182:185], v153 offset:2048
	ds_read_b128 v[186:189], v153 offset:3072
	ds_read_b128 v[190:193], v153 offset:4096
	ds_read_b128 v[194:197], v153 offset:5120
	ds_read_b128 v[198:201], v153 offset:6144
	ds_read_b128 v[202:205], v153 offset:7168
	global_load_lds_dwordx4 v136, s[60:61]
	s_add_i32 m0, s20, 0xe000
	s_nop 0
	s_add_u32 s98, s60, s6
	s_addc_u32 s99, s61, s7
	global_load_lds_dwordx4 v136, s[98:99]
	s_waitcnt vmcnt(8)
	s_waitcnt lgkmcnt(0)
	s_barrier
	s_setprio 1
	s_waitcnt lgkmcnt(0)
	v_mfma_f32_16x16x32_bf16 v[124:127], v[128:131], v[174:177], v[124:127]
	v_mfma_f32_16x16x32_bf16 v[120:123], v[146:149], v[174:177], v[120:123]
	v_mfma_f32_16x16x32_bf16 v[116:119], v[128:131], v[182:185], v[116:119]
	v_mfma_f32_16x16x32_bf16 v[112:115], v[146:149], v[182:185], v[112:115]
	v_mfma_f32_16x16x32_bf16 v[108:111], v[128:131], v[190:193], v[108:111]
	v_mfma_f32_16x16x32_bf16 v[104:107], v[146:149], v[190:193], v[104:107]
	v_mfma_f32_16x16x32_bf16 v[100:103], v[128:131], v[198:201], v[100:103]
	v_mfma_f32_16x16x32_bf16 v[96:99], v[146:149], v[198:201], v[96:99]
	v_mfma_f32_16x16x32_bf16 v[124:127], v[142:145], v[178:181], v[124:127]
	v_mfma_f32_16x16x32_bf16 v[120:123], v[154:157], v[178:181], v[120:123]
	v_mfma_f32_16x16x32_bf16 v[116:119], v[142:145], v[186:189], v[116:119]
	v_mfma_f32_16x16x32_bf16 v[112:115], v[154:157], v[186:189], v[112:115]
	v_mfma_f32_16x16x32_bf16 v[108:111], v[142:145], v[194:197], v[108:111]
	v_mfma_f32_16x16x32_bf16 v[104:107], v[154:157], v[194:197], v[104:107]
	v_mfma_f32_16x16x32_bf16 v[100:103], v[142:145], v[202:205], v[100:103]
	v_mfma_f32_16x16x32_bf16 v[96:99], v[154:157], v[202:205], v[96:99]
	s_setprio 0
	s_setprio 1
	v_mfma_f32_16x16x32_bf16 v[92:95], v[158:161], v[174:177], v[92:95]
	v_mfma_f32_16x16x32_bf16 v[88:91], v[166:169], v[174:177], v[88:91]
	v_mfma_f32_16x16x32_bf16 v[84:87], v[158:161], v[182:185], v[84:87]
	v_mfma_f32_16x16x32_bf16 v[80:83], v[166:169], v[182:185], v[80:83]
	v_mfma_f32_16x16x32_bf16 v[76:79], v[158:161], v[190:193], v[76:79]
	v_mfma_f32_16x16x32_bf16 v[72:75], v[166:169], v[190:193], v[72:75]
	v_mfma_f32_16x16x32_bf16 v[68:71], v[158:161], v[198:201], v[68:71]
	v_mfma_f32_16x16x32_bf16 v[64:67], v[166:169], v[198:201], v[64:67]
	v_mfma_f32_16x16x32_bf16 v[92:95], v[162:165], v[178:181], v[92:95]
	v_mfma_f32_16x16x32_bf16 v[88:91], v[170:173], v[178:181], v[88:91]
	v_mfma_f32_16x16x32_bf16 v[84:87], v[162:165], v[186:189], v[84:87]
	v_mfma_f32_16x16x32_bf16 v[80:83], v[170:173], v[186:189], v[80:83]
	v_mfma_f32_16x16x32_bf16 v[76:79], v[162:165], v[194:197], v[76:79]
	v_mfma_f32_16x16x32_bf16 v[72:75], v[170:173], v[194:197], v[72:75]
	v_mfma_f32_16x16x32_bf16 v[68:71], v[162:165], v[202:205], v[68:71]
	v_mfma_f32_16x16x32_bf16 v[64:67], v[170:173], v[202:205], v[64:67]
	s_setprio 0
	s_barrier
	s_add_i32 s50, s72, s14
	s_mov_b32 m0, s50
	ds_read_b128 v[174:177], v153 offset:16384
	ds_read_b128 v[178:181], v153 offset:17408
	ds_read_b128 v[182:185], v153 offset:18432
	ds_read_b128 v[186:189], v153 offset:19456
	ds_read_b128 v[190:193], v153 offset:20480
	ds_read_b128 v[194:197], v153 offset:21504
	ds_read_b128 v[198:201], v153 offset:22528
	ds_read_b128 v[202:205], v153 offset:23552
	global_load_lds_dwordx4 v134, s[78:79]
	s_add_i32 m0, s50, 0x2000
	s_add_i32 s50, s73, s14
	s_add_u32 s98, s78, s6
	s_addc_u32 s99, s79, s7
	global_load_lds_dwordx4 v134, s[98:99]
	s_mov_b32 m0, s50
	s_nop 0
	s_add_u32 s98, s78, s8
	s_addc_u32 s99, s79, s9
	global_load_lds_dwordx4 v134, s[98:99]
	s_add_i32 m0, s50, 0x2000
	s_nop 0
	s_add_u32 s98, s78, s10
	s_addc_u32 s99, s79, s11
	global_load_lds_dwordx4 v134, s[98:99]
	s_mov_b32 m0, s20
	s_nop 0
	global_load_lds_dwordx4 v132, s[76:77]
	s_mov_b32 m0, s21
	s_nop 0
	s_add_u32 s98, s76, s6
	s_addc_u32 s99, s77, s7
	global_load_lds_dwordx4 v132, s[98:99]
	s_waitcnt vmcnt(8)
	s_waitcnt lgkmcnt(0)
	s_barrier
	s_setprio 1
	s_waitcnt lgkmcnt(0)
	v_mfma_f32_16x16x32_bf16 v[60:63], v[128:131], v[174:177], v[60:63]
	v_mfma_f32_16x16x32_bf16 v[56:59], v[146:149], v[174:177], v[56:59]
	v_mfma_f32_16x16x32_bf16 v[52:55], v[128:131], v[182:185], v[52:55]
	v_mfma_f32_16x16x32_bf16 v[48:51], v[146:149], v[182:185], v[48:51]
	v_mfma_f32_16x16x32_bf16 v[44:47], v[128:131], v[190:193], v[44:47]
	v_mfma_f32_16x16x32_bf16 v[40:43], v[146:149], v[190:193], v[40:43]
	v_mfma_f32_16x16x32_bf16 v[36:39], v[128:131], v[198:201], v[36:39]
	v_mfma_f32_16x16x32_bf16 v[32:35], v[146:149], v[198:201], v[32:35]
	v_mfma_f32_16x16x32_bf16 v[60:63], v[142:145], v[178:181], v[60:63]
	v_mfma_f32_16x16x32_bf16 v[56:59], v[154:157], v[178:181], v[56:59]
	v_mfma_f32_16x16x32_bf16 v[52:55], v[142:145], v[186:189], v[52:55]
	v_mfma_f32_16x16x32_bf16 v[48:51], v[154:157], v[186:189], v[48:51]
	v_mfma_f32_16x16x32_bf16 v[44:47], v[142:145], v[194:197], v[44:47]
	v_mfma_f32_16x16x32_bf16 v[40:43], v[154:157], v[194:197], v[40:43]
	v_mfma_f32_16x16x32_bf16 v[36:39], v[142:145], v[202:205], v[36:39]
	v_mfma_f32_16x16x32_bf16 v[32:35], v[154:157], v[202:205], v[32:35]
	s_setprio 0
	s_setprio 1
	v_mfma_f32_16x16x32_bf16 v[28:31], v[158:161], v[174:177], v[28:31]
	v_mfma_f32_16x16x32_bf16 v[24:27], v[166:169], v[174:177], v[24:27]
	v_mfma_f32_16x16x32_bf16 v[20:23], v[158:161], v[182:185], v[20:23]
	v_mfma_f32_16x16x32_bf16 v[16:19], v[166:169], v[182:185], v[16:19]
	v_mfma_f32_16x16x32_bf16 v[12:15], v[158:161], v[190:193], v[12:15]
	v_mfma_f32_16x16x32_bf16 v[8:11], v[166:169], v[190:193], v[8:11]
	v_mfma_f32_16x16x32_bf16 v[4:7], v[158:161], v[198:201], v[4:7]
	v_mfma_f32_16x16x32_bf16 v[0:3], v[166:169], v[198:201], v[0:3]
	v_mfma_f32_16x16x32_bf16 v[28:31], v[162:165], v[178:181], v[28:31]
	v_mfma_f32_16x16x32_bf16 v[24:27], v[170:173], v[178:181], v[24:27]
	v_mfma_f32_16x16x32_bf16 v[20:23], v[162:165], v[186:189], v[20:23]
	v_mfma_f32_16x16x32_bf16 v[16:19], v[170:173], v[186:189], v[16:19]
	v_mfma_f32_16x16x32_bf16 v[12:15], v[162:165], v[194:197], v[12:15]
	v_mfma_f32_16x16x32_bf16 v[8:11], v[170:173], v[194:197], v[8:11]
	v_mfma_f32_16x16x32_bf16 v[4:7], v[162:165], v[202:205], v[4:7]
	v_mfma_f32_16x16x32_bf16 v[0:3], v[170:173], v[202:205], v[0:3]
	s_setprio 0
	s_barrier
	s_add_i32 s50, 0, 0x18000
	s_add_i32 s51, 0, 0x1c000
	v_add_u32_e32 v154, s50, v150
	v_add_u32_e32 v170, s51, v150
	ds_read_b128 v[128:131], v154
	ds_read_b128 v[142:145], v154 offset:1024
	ds_read_b128 v[146:149], v154 offset:2048
	ds_read_b128 v[154:157], v154 offset:3072
	ds_read_b128 v[158:161], v170
	ds_read_b128 v[162:165], v170 offset:1024
	ds_read_b128 v[166:169], v170 offset:2048
	ds_read_b128 v[170:173], v170 offset:3072
	s_mov_b32 m0, s33
	ds_read_b128 v[174:177], v153 offset:32768
	ds_read_b128 v[178:181], v153 offset:33792
	ds_read_b128 v[182:185], v153 offset:34816
	ds_read_b128 v[186:189], v153 offset:35840
	ds_read_b128 v[190:193], v153 offset:36864
	ds_read_b128 v[194:197], v153 offset:37888
	ds_read_b128 v[198:201], v153 offset:38912
	ds_read_b128 v[202:205], v153 offset:39936
	s_add_u32 s98, s76, s8
	s_addc_u32 s99, s77, s9
	global_load_lds_dwordx4 v132, s[98:99]
	s_mov_b32 m0, s64
	s_nop 0
	s_add_u32 s98, s76, s10
	s_addc_u32 s99, s77, s11
	global_load_lds_dwordx4 v132, s[98:99]
	s_waitcnt vmcnt(8)
	s_waitcnt lgkmcnt(0)
	s_barrier
	s_setprio 1
	s_waitcnt lgkmcnt(0)
	v_mfma_f32_16x16x32_bf16 v[124:127], v[128:131], v[174:177], v[124:127]
	v_mfma_f32_16x16x32_bf16 v[120:123], v[146:149], v[174:177], v[120:123]
	v_mfma_f32_16x16x32_bf16 v[116:119], v[128:131], v[182:185], v[116:119]
	v_mfma_f32_16x16x32_bf16 v[112:115], v[146:149], v[182:185], v[112:115]
	v_mfma_f32_16x16x32_bf16 v[108:111], v[128:131], v[190:193], v[108:111]
	v_mfma_f32_16x16x32_bf16 v[104:107], v[146:149], v[190:193], v[104:107]
	v_mfma_f32_16x16x32_bf16 v[100:103], v[128:131], v[198:201], v[100:103]
	v_mfma_f32_16x16x32_bf16 v[96:99], v[146:149], v[198:201], v[96:99]
	v_mfma_f32_16x16x32_bf16 v[124:127], v[142:145], v[178:181], v[124:127]
	v_mfma_f32_16x16x32_bf16 v[120:123], v[154:157], v[178:181], v[120:123]
	v_mfma_f32_16x16x32_bf16 v[116:119], v[142:145], v[186:189], v[116:119]
	v_mfma_f32_16x16x32_bf16 v[112:115], v[154:157], v[186:189], v[112:115]
	v_mfma_f32_16x16x32_bf16 v[108:111], v[142:145], v[194:197], v[108:111]
	v_mfma_f32_16x16x32_bf16 v[104:107], v[154:157], v[194:197], v[104:107]
	v_mfma_f32_16x16x32_bf16 v[100:103], v[142:145], v[202:205], v[100:103]
	v_mfma_f32_16x16x32_bf16 v[96:99], v[154:157], v[202:205], v[96:99]
	s_setprio 0
	s_setprio 1
	v_mfma_f32_16x16x32_bf16 v[92:95], v[158:161], v[174:177], v[92:95]
	v_mfma_f32_16x16x32_bf16 v[88:91], v[166:169], v[174:177], v[88:91]
	v_mfma_f32_16x16x32_bf16 v[84:87], v[158:161], v[182:185], v[84:87]
	v_mfma_f32_16x16x32_bf16 v[80:83], v[166:169], v[182:185], v[80:83]
	v_mfma_f32_16x16x32_bf16 v[76:79], v[158:161], v[190:193], v[76:79]
	v_mfma_f32_16x16x32_bf16 v[72:75], v[166:169], v[190:193], v[72:75]
	v_mfma_f32_16x16x32_bf16 v[68:71], v[158:161], v[198:201], v[68:71]
	v_mfma_f32_16x16x32_bf16 v[64:67], v[166:169], v[198:201], v[64:67]
	v_mfma_f32_16x16x32_bf16 v[92:95], v[162:165], v[178:181], v[92:95]
	v_mfma_f32_16x16x32_bf16 v[88:91], v[170:173], v[178:181], v[88:91]
	v_mfma_f32_16x16x32_bf16 v[84:87], v[162:165], v[186:189], v[84:87]
	v_mfma_f32_16x16x32_bf16 v[80:83], v[170:173], v[186:189], v[80:83]
	v_mfma_f32_16x16x32_bf16 v[76:79], v[162:165], v[194:197], v[76:79]
	v_mfma_f32_16x16x32_bf16 v[72:75], v[170:173], v[194:197], v[72:75]
	v_mfma_f32_16x16x32_bf16 v[68:71], v[162:165], v[202:205], v[68:71]
	v_mfma_f32_16x16x32_bf16 v[64:67], v[170:173], v[202:205], v[64:67]
	s_setprio 0
	s_barrier
	s_add_i32 s50, s50, s14
	s_mov_b32 m0, s50
	ds_read_b128 v[174:177], v153 offset:49152
	ds_read_b128 v[178:181], v153 offset:50176
	ds_read_b128 v[182:185], v153 offset:51200
	ds_read_b128 v[186:189], v153 offset:52224
	ds_read_b128 v[190:193], v153 offset:53248
	ds_read_b128 v[194:197], v153 offset:54272
	ds_read_b128 v[198:201], v153 offset:55296
	ds_read_b128 v[202:205], v153 offset:56320
	s_add_u32 s98, s78, s24
	s_addc_u32 s99, s79, s25
	global_load_lds_dwordx4 v134, s[98:99]
	s_add_i32 m0, s50, 0x2000
	s_add_i32 s50, s51, s14
	s_add_u32 s98, s78, s34
	s_addc_u32 s99, s79, s35
	global_load_lds_dwordx4 v134, s[98:99]
	s_mov_b32 m0, s50
	s_add_u32 s98, s78, s36
	s_addc_u32 s99, s79, s37
	global_load_lds_dwordx4 v134, s[98:99]
	s_add_i32 m0, s50, 0x2000
	s_nop 0
	s_add_u32 s98, s78, s38
	s_addc_u32 s99, s79, s39
	global_load_lds_dwordx4 v134, s[98:99]
	s_mov_b32 m0, s66
	s_nop 0
	s_add_u32 s98, s76, s24
	s_addc_u32 s99, s77, s25
	global_load_lds_dwordx4 v132, s[98:99]
	s_mov_b32 m0, s67
	s_nop 0
	s_add_u32 s98, s76, s34
	s_addc_u32 s99, s77, s35
	global_load_lds_dwordx4 v132, s[98:99]
	s_waitcnt vmcnt(8)
	s_waitcnt lgkmcnt(0)
	s_barrier
	s_setprio 1
	s_waitcnt lgkmcnt(0)
	v_mfma_f32_16x16x32_bf16 v[60:63], v[128:131], v[174:177], v[60:63]
	v_mfma_f32_16x16x32_bf16 v[56:59], v[146:149], v[174:177], v[56:59]
	v_mfma_f32_16x16x32_bf16 v[52:55], v[128:131], v[182:185], v[52:55]
	v_mfma_f32_16x16x32_bf16 v[48:51], v[146:149], v[182:185], v[48:51]
	v_mfma_f32_16x16x32_bf16 v[44:47], v[128:131], v[190:193], v[44:47]
	v_mfma_f32_16x16x32_bf16 v[40:43], v[146:149], v[190:193], v[40:43]
	v_mfma_f32_16x16x32_bf16 v[36:39], v[128:131], v[198:201], v[36:39]
	v_mfma_f32_16x16x32_bf16 v[32:35], v[146:149], v[198:201], v[32:35]
	v_mfma_f32_16x16x32_bf16 v[60:63], v[142:145], v[178:181], v[60:63]
	v_mfma_f32_16x16x32_bf16 v[56:59], v[154:157], v[178:181], v[56:59]
	v_mfma_f32_16x16x32_bf16 v[52:55], v[142:145], v[186:189], v[52:55]
	v_mfma_f32_16x16x32_bf16 v[48:51], v[154:157], v[186:189], v[48:51]
	v_mfma_f32_16x16x32_bf16 v[44:47], v[142:145], v[194:197], v[44:47]
	v_mfma_f32_16x16x32_bf16 v[40:43], v[154:157], v[194:197], v[40:43]
	v_mfma_f32_16x16x32_bf16 v[36:39], v[142:145], v[202:205], v[36:39]
	v_mfma_f32_16x16x32_bf16 v[32:35], v[154:157], v[202:205], v[32:35]
	s_setprio 0
	s_setprio 1
	v_mfma_f32_16x16x32_bf16 v[28:31], v[158:161], v[174:177], v[28:31]
	v_mfma_f32_16x16x32_bf16 v[24:27], v[166:169], v[174:177], v[24:27]
	v_mfma_f32_16x16x32_bf16 v[20:23], v[158:161], v[182:185], v[20:23]
	v_mfma_f32_16x16x32_bf16 v[16:19], v[166:169], v[182:185], v[16:19]
	v_mfma_f32_16x16x32_bf16 v[12:15], v[158:161], v[190:193], v[12:15]
	v_mfma_f32_16x16x32_bf16 v[8:11], v[166:169], v[190:193], v[8:11]
	v_mfma_f32_16x16x32_bf16 v[4:7], v[158:161], v[198:201], v[4:7]
	v_mfma_f32_16x16x32_bf16 v[0:3], v[166:169], v[198:201], v[0:3]
	v_mfma_f32_16x16x32_bf16 v[28:31], v[162:165], v[178:181], v[28:31]
	v_mfma_f32_16x16x32_bf16 v[24:27], v[170:173], v[178:181], v[24:27]
	v_mfma_f32_16x16x32_bf16 v[20:23], v[162:165], v[186:189], v[20:23]
	v_mfma_f32_16x16x32_bf16 v[16:19], v[170:173], v[186:189], v[16:19]
	v_mfma_f32_16x16x32_bf16 v[12:15], v[162:165], v[194:197], v[12:15]
	v_mfma_f32_16x16x32_bf16 v[8:11], v[170:173], v[194:197], v[8:11]
	v_mfma_f32_16x16x32_bf16 v[4:7], v[162:165], v[202:205], v[4:7]
	v_mfma_f32_16x16x32_bf16 v[0:3], v[170:173], v[202:205], v[0:3]
	s_setprio 0
	s_barrier
	s_add_i32 s62, s62, 2
	s_add_u32 s74, s74, 0x100
	s_addc_u32 s75, s75, 0
	s_add_u32 s60, s60, 0x100
	s_addc_u32 s61, s61, 0
	s_cmp_gt_u32 s62, 61
	s_cbranch_scc0 .LBB0_627
	s_and_b64 vcc, exec, s[40:41]
	s_cbranch_vccz .LBB0_630
	s_barrier

.LBB0_800:
	ds_read_b128 v[128:131], v187
	ds_read_b128 v[132:135], v187 offset:1024
	ds_read_b128 v[136:139], v187 offset:2048
	ds_read_b128 v[140:143], v187 offset:3072
	ds_read_b128 v[144:147], v188
	ds_read_b128 v[148:151], v188 offset:1024
	ds_read_b128 v[152:155], v188 offset:2048
	ds_read_b128 v[156:159], v188 offset:3072
	s_add_u32 s9, s6, 0xfff80080
	s_addc_u32 s50, s7, -1
	s_cmp_eq_u32 s8, 28
	s_cselect_b32 vcc_hi, s5, s50
	s_cselect_b32 vcc_lo, s10, s9
	s_cselect_b32 s51, s11, s78
	s_cselect_b32 s50, s73, s75
	s_add_i32 m0, s65, 0xc000
	ds_read_b128 v[160:163], v189
	ds_read_b128 v[164:167], v189 offset:1024
	ds_read_b128 v[168:171], v189 offset:2048
	ds_read_b128 v[192:195], v189 offset:3072
	ds_read_b128 v[196:199], v189 offset:4096
	ds_read_b128 v[200:203], v189 offset:5120
	ds_read_b128 v[204:207], v189 offset:6144
	ds_read_b128 v[208:211], v189 offset:7168
	global_load_lds_dwordx4 v178, s[6:7]
	s_add_i32 m0, s65, 0xe000
	s_nop 0
	s_add_u32 s98, s6, s36
	s_addc_u32 s99, s7, s37
	global_load_lds_dwordx4 v178, s[98:99]
	s_waitcnt vmcnt(8)
	s_waitcnt lgkmcnt(0)
	s_barrier
	s_setprio 1
	s_waitcnt lgkmcnt(0)
	v_mfma_i32_16x16x64_i8 v[84:87], v[128:131], v[160:163], v[84:87]
	v_mfma_i32_16x16x64_i8 v[16:19], v[136:139], v[160:163], v[16:19]
	v_mfma_i32_16x16x64_i8 v[88:91], v[128:131], v[168:171], v[88:91]
	v_mfma_i32_16x16x64_i8 v[20:23], v[136:139], v[168:171], v[20:23]
	v_mfma_i32_16x16x64_i8 v[92:95], v[128:131], v[196:199], v[92:95]
	v_mfma_i32_16x16x64_i8 v[24:27], v[136:139], v[196:199], v[24:27]
	v_mfma_i32_16x16x64_i8 v[96:99], v[128:131], v[204:207], v[96:99]
	v_mfma_i32_16x16x64_i8 v[28:31], v[136:139], v[204:207], v[28:31]
	v_mfma_i32_16x16x64_i8 v[84:87], v[132:135], v[164:167], v[84:87]
	v_mfma_i32_16x16x64_i8 v[16:19], v[140:143], v[164:167], v[16:19]
	v_mfma_i32_16x16x64_i8 v[88:91], v[132:135], v[192:195], v[88:91]
	v_mfma_i32_16x16x64_i8 v[20:23], v[140:143], v[192:195], v[20:23]
	v_mfma_i32_16x16x64_i8 v[92:95], v[132:135], v[200:203], v[92:95]
	v_mfma_i32_16x16x64_i8 v[24:27], v[140:143], v[200:203], v[24:27]
	v_mfma_i32_16x16x64_i8 v[96:99], v[132:135], v[208:211], v[96:99]
	v_mfma_i32_16x16x64_i8 v[28:31], v[140:143], v[208:211], v[28:31]
	s_setprio 0
	s_setprio 1
	v_mfma_i32_16x16x64_i8 v[124:127], v[144:147], v[160:163], v[124:127]
	v_mfma_i32_16x16x64_i8 v[68:71], v[152:155], v[160:163], v[68:71]
	v_mfma_i32_16x16x64_i8 v[120:123], v[144:147], v[168:171], v[120:123]
	v_mfma_i32_16x16x64_i8 v[72:75], v[152:155], v[168:171], v[72:75]
	v_mfma_i32_16x16x64_i8 v[116:119], v[144:147], v[196:199], v[116:119]
	v_mfma_i32_16x16x64_i8 v[80:83], v[152:155], v[196:199], v[80:83]
	v_mfma_i32_16x16x64_i8 v[112:115], v[144:147], v[204:207], v[112:115]
	v_mfma_i32_16x16x64_i8 v[60:63], v[152:155], v[204:207], v[60:63]
	v_mfma_i32_16x16x64_i8 v[124:127], v[148:151], v[164:167], v[124:127]
	v_mfma_i32_16x16x64_i8 v[68:71], v[156:159], v[164:167], v[68:71]
	v_mfma_i32_16x16x64_i8 v[120:123], v[148:151], v[192:195], v[120:123]
	v_mfma_i32_16x16x64_i8 v[72:75], v[156:159], v[192:195], v[72:75]
	v_mfma_i32_16x16x64_i8 v[116:119], v[148:151], v[200:203], v[116:119]
	v_mfma_i32_16x16x64_i8 v[80:83], v[156:159], v[200:203], v[80:83]
	v_mfma_i32_16x16x64_i8 v[112:115], v[148:151], v[208:211], v[112:115]
	v_mfma_i32_16x16x64_i8 v[60:63], v[156:159], v[208:211], v[60:63]
	s_setprio 0
	s_barrier
	s_add_i32 s9, s80, s33
	s_mov_b64 s[100:101], s[50:51]
	s_mov_b32 m0, s9
	ds_read_b128 v[160:163], v189 offset:16384
	ds_read_b128 v[164:167], v189 offset:17408
	ds_read_b128 v[168:171], v189 offset:18432
	ds_read_b128 v[192:195], v189 offset:19456
	ds_read_b128 v[196:199], v189 offset:20480
	ds_read_b128 v[200:203], v189 offset:21504
	ds_read_b128 v[204:207], v189 offset:22528
	ds_read_b128 v[208:211], v189 offset:23552
	global_load_lds_dwordx4 v174, s[50:51]
	s_add_i32 m0, s9, 0x2000
	s_add_i32 s9, s81, s33
	s_add_u32 s98, s50, s36
	s_addc_u32 s99, s51, s37
	global_load_lds_dwordx4 v174, s[98:99]
	s_mov_b32 m0, s9
	s_nop 0
	s_add_u32 s98, s50, s38
	s_addc_u32 s99, s51, s39
	global_load_lds_dwordx4 v174, s[98:99]
	s_add_i32 m0, s9, 0x2000
	s_nop 0
	s_add_u32 s98, s50, s40
	s_addc_u32 s99, s51, s41
	global_load_lds_dwordx4 v174, s[98:99]
	s_mov_b32 m0, s65
	s_nop 0
	global_load_lds_dwordx4 v172, vcc
	s_mov_b32 m0, s67
	s_nop 0
	s_add_u32 s98, vcc_lo, s36
	s_addc_u32 s99, vcc_hi, s37
	global_load_lds_dwordx4 v172, s[98:99]
	s_waitcnt vmcnt(8)
	s_waitcnt lgkmcnt(0)
	s_barrier
	s_setprio 1
	s_waitcnt lgkmcnt(0)
	v_mfma_i32_16x16x64_i8 v[48:51], v[128:131], v[160:163], v[48:51]
	v_mfma_i32_16x16x64_i8 v[0:3], v[136:139], v[160:163], v[0:3]
	v_mfma_i32_16x16x64_i8 v[52:55], v[128:131], v[168:171], v[52:55]
	v_mfma_i32_16x16x64_i8 v[4:7], v[136:139], v[168:171], v[4:7]
	v_mfma_i32_16x16x64_i8 v[56:59], v[128:131], v[196:199], v[56:59]
	v_mfma_i32_16x16x64_i8 v[8:11], v[136:139], v[196:199], v[8:11]
	v_mfma_i32_16x16x64_i8 v[64:67], v[128:131], v[204:207], v[64:67]
	v_mfma_i32_16x16x64_i8 v[12:15], v[136:139], v[204:207], v[12:15]
	v_mfma_i32_16x16x64_i8 v[48:51], v[132:135], v[164:167], v[48:51]
	v_mfma_i32_16x16x64_i8 v[0:3], v[140:143], v[164:167], v[0:3]
	v_mfma_i32_16x16x64_i8 v[52:55], v[132:135], v[192:195], v[52:55]
	v_mfma_i32_16x16x64_i8 v[4:7], v[140:143], v[192:195], v[4:7]
	v_mfma_i32_16x16x64_i8 v[56:59], v[132:135], v[200:203], v[56:59]
	v_mfma_i32_16x16x64_i8 v[8:11], v[140:143], v[200:203], v[8:11]
	v_mfma_i32_16x16x64_i8 v[64:67], v[132:135], v[208:211], v[64:67]
	v_mfma_i32_16x16x64_i8 v[12:15], v[140:143], v[208:211], v[12:15]
	s_setprio 0
	s_setprio 1
	v_mfma_i32_16x16x64_i8 v[108:111], v[144:147], v[160:163], v[108:111]
	v_mfma_i32_16x16x64_i8 v[44:47], v[152:155], v[160:163], v[44:47]
	v_mfma_i32_16x16x64_i8 v[104:107], v[144:147], v[168:171], v[104:107]
	v_mfma_i32_16x16x64_i8 v[40:43], v[152:155], v[168:171], v[40:43]
	v_mfma_i32_16x16x64_i8 v[100:103], v[144:147], v[196:199], v[100:103]
	v_mfma_i32_16x16x64_i8 v[32:35], v[152:155], v[196:199], v[32:35]
	v_mfma_i32_16x16x64_i8 v[76:79], v[144:147], v[204:207], v[76:79]
	v_mfma_i32_16x16x64_i8 v[36:39], v[152:155], v[204:207], v[36:39]
	v_mfma_i32_16x16x64_i8 v[108:111], v[148:151], v[164:167], v[108:111]
	v_mfma_i32_16x16x64_i8 v[44:47], v[156:159], v[164:167], v[44:47]
	v_mfma_i32_16x16x64_i8 v[104:107], v[148:151], v[192:195], v[104:107]
	v_mfma_i32_16x16x64_i8 v[40:43], v[156:159], v[192:195], v[40:43]
	v_mfma_i32_16x16x64_i8 v[100:103], v[148:151], v[200:203], v[100:103]
	v_mfma_i32_16x16x64_i8 v[32:35], v[156:159], v[200:203], v[32:35]
	v_mfma_i32_16x16x64_i8 v[76:79], v[148:151], v[208:211], v[76:79]
	v_mfma_i32_16x16x64_i8 v[36:39], v[156:159], v[208:211], v[36:39]
	s_setprio 0
	s_barrier
	s_add_i32 s9, 0, 0x18000
	s_add_i32 s50, 0, 0x1c000
	v_add_u32_e32 v140, s9, v186
	v_add_u32_e32 v156, s50, v186
	ds_read_b128 v[128:131], v140
	ds_read_b128 v[132:135], v140 offset:1024
	ds_read_b128 v[136:139], v140 offset:2048
	ds_read_b128 v[140:143], v140 offset:3072
	ds_read_b128 v[144:147], v156
	ds_read_b128 v[148:151], v156 offset:1024
	ds_read_b128 v[152:155], v156 offset:2048
	ds_read_b128 v[156:159], v156 offset:3072
	s_mov_b32 m0, s71
	ds_read_b128 v[160:163], v189 offset:32768
	ds_read_b128 v[164:167], v189 offset:33792
	ds_read_b128 v[168:171], v189 offset:34816
	ds_read_b128 v[192:195], v189 offset:35840
	ds_read_b128 v[196:199], v189 offset:36864
	ds_read_b128 v[200:203], v189 offset:37888
	ds_read_b128 v[204:207], v189 offset:38912
	ds_read_b128 v[208:211], v189 offset:39936
	s_add_u32 s98, vcc_lo, s38
	s_addc_u32 s99, vcc_hi, s39
	global_load_lds_dwordx4 v172, s[98:99]
	s_mov_b32 m0, s82
	s_nop 0
	s_add_u32 s98, vcc_lo, s40
	s_addc_u32 s99, vcc_hi, s41
	global_load_lds_dwordx4 v172, s[98:99]
	s_waitcnt vmcnt(8)
	s_waitcnt lgkmcnt(0)
	s_barrier
	s_setprio 1
	s_waitcnt lgkmcnt(0)
	v_mfma_i32_16x16x64_i8 v[84:87], v[128:131], v[160:163], v[84:87]
	v_mfma_i32_16x16x64_i8 v[16:19], v[136:139], v[160:163], v[16:19]
	v_mfma_i32_16x16x64_i8 v[88:91], v[128:131], v[168:171], v[88:91]
	v_mfma_i32_16x16x64_i8 v[20:23], v[136:139], v[168:171], v[20:23]
	v_mfma_i32_16x16x64_i8 v[92:95], v[128:131], v[196:199], v[92:95]
	v_mfma_i32_16x16x64_i8 v[24:27], v[136:139], v[196:199], v[24:27]
	v_mfma_i32_16x16x64_i8 v[96:99], v[128:131], v[204:207], v[96:99]
	v_mfma_i32_16x16x64_i8 v[28:31], v[136:139], v[204:207], v[28:31]
	v_mfma_i32_16x16x64_i8 v[84:87], v[132:135], v[164:167], v[84:87]
	v_mfma_i32_16x16x64_i8 v[16:19], v[140:143], v[164:167], v[16:19]
	v_mfma_i32_16x16x64_i8 v[88:91], v[132:135], v[192:195], v[88:91]
	v_mfma_i32_16x16x64_i8 v[20:23], v[140:143], v[192:195], v[20:23]
	v_mfma_i32_16x16x64_i8 v[92:95], v[132:135], v[200:203], v[92:95]
	v_mfma_i32_16x16x64_i8 v[24:27], v[140:143], v[200:203], v[24:27]
	v_mfma_i32_16x16x64_i8 v[96:99], v[132:135], v[208:211], v[96:99]
	v_mfma_i32_16x16x64_i8 v[28:31], v[140:143], v[208:211], v[28:31]
	s_setprio 0
	s_setprio 1
	v_mfma_i32_16x16x64_i8 v[124:127], v[144:147], v[160:163], v[124:127]
	v_mfma_i32_16x16x64_i8 v[68:71], v[152:155], v[160:163], v[68:71]
	v_mfma_i32_16x16x64_i8 v[120:123], v[144:147], v[168:171], v[120:123]
	v_mfma_i32_16x16x64_i8 v[72:75], v[152:155], v[168:171], v[72:75]
	v_mfma_i32_16x16x64_i8 v[116:119], v[144:147], v[196:199], v[116:119]
	v_mfma_i32_16x16x64_i8 v[80:83], v[152:155], v[196:199], v[80:83]
	v_mfma_i32_16x16x64_i8 v[112:115], v[144:147], v[204:207], v[112:115]
	v_mfma_i32_16x16x64_i8 v[60:63], v[152:155], v[204:207], v[60:63]
	v_mfma_i32_16x16x64_i8 v[124:127], v[148:151], v[164:167], v[124:127]
	v_mfma_i32_16x16x64_i8 v[68:71], v[156:159], v[164:167], v[68:71]
	v_mfma_i32_16x16x64_i8 v[120:123], v[148:151], v[192:195], v[120:123]
	v_mfma_i32_16x16x64_i8 v[72:75], v[156:159], v[192:195], v[72:75]
	v_mfma_i32_16x16x64_i8 v[116:119], v[148:151], v[200:203], v[116:119]
	v_mfma_i32_16x16x64_i8 v[80:83], v[156:159], v[200:203], v[80:83]
	v_mfma_i32_16x16x64_i8 v[112:115], v[148:151], v[208:211], v[112:115]
	v_mfma_i32_16x16x64_i8 v[60:63], v[156:159], v[208:211], v[60:63]
	s_setprio 0
	s_barrier
	s_add_i32 s9, s9, s33
	s_mov_b32 m0, s9
	ds_read_b128 v[160:163], v189 offset:49152
	ds_read_b128 v[164:167], v189 offset:50176
	ds_read_b128 v[168:171], v189 offset:51200
	ds_read_b128 v[192:195], v189 offset:52224
	ds_read_b128 v[196:199], v189 offset:53248
	ds_read_b128 v[200:203], v189 offset:54272
	ds_read_b128 v[204:207], v189 offset:55296
	ds_read_b128 v[208:211], v189 offset:56320
	s_add_u32 s98, s100, s44
	s_addc_u32 s99, s101, s45
	global_load_lds_dwordx4 v174, s[98:99]
	s_add_i32 m0, s9, 0x2000
	s_add_i32 s9, s50, s33
	s_add_u32 s98, s100, s46
	s_addc_u32 s99, s101, s47
	global_load_lds_dwordx4 v174, s[98:99]
	s_mov_b32 m0, s9
	s_add_u32 s98, s100, s48
	s_addc_u32 s99, s101, s49
	global_load_lds_dwordx4 v174, s[98:99]
	s_add_i32 m0, s9, 0x2000
	s_nop 0
	s_add_u32 s98, s100, s52
	s_addc_u32 s99, s101, s53
	global_load_lds_dwordx4 v174, s[98:99]
	s_mov_b32 m0, s90
	s_nop 0
	s_add_u32 s98, vcc_lo, s44
	s_addc_u32 s99, vcc_hi, s45
	global_load_lds_dwordx4 v172, s[98:99]
	s_mov_b32 m0, s91
	s_nop 0
	s_add_u32 s98, vcc_lo, s46
	s_addc_u32 s99, vcc_hi, s47
	global_load_lds_dwordx4 v172, s[98:99]
	s_waitcnt vmcnt(8)
	s_waitcnt lgkmcnt(0)
	s_barrier
	s_setprio 1
	s_waitcnt lgkmcnt(0)
	v_mfma_i32_16x16x64_i8 v[48:51], v[128:131], v[160:163], v[48:51]
	v_mfma_i32_16x16x64_i8 v[0:3], v[136:139], v[160:163], v[0:3]
	v_mfma_i32_16x16x64_i8 v[52:55], v[128:131], v[168:171], v[52:55]
	v_mfma_i32_16x16x64_i8 v[4:7], v[136:139], v[168:171], v[4:7]
	v_mfma_i32_16x16x64_i8 v[56:59], v[128:131], v[196:199], v[56:59]
	v_mfma_i32_16x16x64_i8 v[8:11], v[136:139], v[196:199], v[8:11]
	v_mfma_i32_16x16x64_i8 v[64:67], v[128:131], v[204:207], v[64:67]
	v_mfma_i32_16x16x64_i8 v[12:15], v[136:139], v[204:207], v[12:15]
	v_mfma_i32_16x16x64_i8 v[48:51], v[132:135], v[164:167], v[48:51]
	v_mfma_i32_16x16x64_i8 v[0:3], v[140:143], v[164:167], v[0:3]
	v_mfma_i32_16x16x64_i8 v[52:55], v[132:135], v[192:195], v[52:55]
	v_mfma_i32_16x16x64_i8 v[4:7], v[140:143], v[192:195], v[4:7]
	v_mfma_i32_16x16x64_i8 v[56:59], v[132:135], v[200:203], v[56:59]
	v_mfma_i32_16x16x64_i8 v[8:11], v[140:143], v[200:203], v[8:11]
	v_mfma_i32_16x16x64_i8 v[64:67], v[132:135], v[208:211], v[64:67]
	v_mfma_i32_16x16x64_i8 v[12:15], v[140:143], v[208:211], v[12:15]
	s_setprio 0
	s_setprio 1
	v_mfma_i32_16x16x64_i8 v[108:111], v[144:147], v[160:163], v[108:111]
	v_mfma_i32_16x16x64_i8 v[44:47], v[152:155], v[160:163], v[44:47]
	v_mfma_i32_16x16x64_i8 v[104:107], v[144:147], v[168:171], v[104:107]
	v_mfma_i32_16x16x64_i8 v[40:43], v[152:155], v[168:171], v[40:43]
	v_mfma_i32_16x16x64_i8 v[100:103], v[144:147], v[196:199], v[100:103]
	v_mfma_i32_16x16x64_i8 v[32:35], v[152:155], v[196:199], v[32:35]
	v_mfma_i32_16x16x64_i8 v[76:79], v[144:147], v[204:207], v[76:79]
	v_mfma_i32_16x16x64_i8 v[36:39], v[152:155], v[204:207], v[36:39]
	v_mfma_i32_16x16x64_i8 v[108:111], v[148:151], v[164:167], v[108:111]
	v_mfma_i32_16x16x64_i8 v[44:47], v[156:159], v[164:167], v[44:47]
	v_mfma_i32_16x16x64_i8 v[104:107], v[148:151], v[192:195], v[104:107]
	v_mfma_i32_16x16x64_i8 v[40:43], v[156:159], v[192:195], v[40:43]
	v_mfma_i32_16x16x64_i8 v[100:103], v[148:151], v[200:203], v[100:103]
	v_mfma_i32_16x16x64_i8 v[32:35], v[156:159], v[200:203], v[32:35]
	v_mfma_i32_16x16x64_i8 v[76:79], v[148:151], v[208:211], v[76:79]
	v_mfma_i32_16x16x64_i8 v[36:39], v[156:159], v[208:211], v[36:39]
	s_setprio 0
	s_barrier
	s_add_i32 s8, s8, 2
	s_add_u32 s75, s75, 0x100
	s_addc_u32 s78, s78, 0
	s_add_u32 s6, s6, 0x100
	s_addc_u32 s7, s7, 0
	s_cmp_gt_u32 s8, 29
	s_cbranch_scc0 .LBB0_800
	s_and_b64 vcc, exec, s[54:55]
	s_cbranch_vccz .LBB0_803
	s_barrier

.LBB0_1034:
	ds_read_b128 v[138:141], v151
	ds_read_b128 v[142:145], v151 offset:1024
	ds_read_b128 v[146:149], v151 offset:2048
	ds_read_b128 v[154:157], v151 offset:3072
	ds_read_b128 v[158:161], v152
	ds_read_b128 v[162:165], v152 offset:1024
	ds_read_b128 v[166:169], v152 offset:2048
	ds_read_b128 v[170:173], v152 offset:3072
	s_add_u32 s47, s44, 0xffd50080
	s_addc_u32 s64, s45, -1
	s_cmpk_eq_i32 s46, 0xa8
	s_cselect_b32 s65, s5, s64
	s_cselect_b32 s64, s4, s47
	s_cselect_b32 s67, s43, s63
	s_cselect_b32 s66, s42, s62
	s_add_i32 m0, s25, 0xc000
	ds_read_b128 v[174:177], v153
	ds_read_b128 v[178:181], v153 offset:1024
	ds_read_b128 v[182:185], v153 offset:2048
	ds_read_b128 v[186:189], v153 offset:3072
	ds_read_b128 v[190:193], v153 offset:4096
	ds_read_b128 v[194:197], v153 offset:5120
	ds_read_b128 v[198:201], v153 offset:6144
	ds_read_b128 v[202:205], v153 offset:7168
	global_load_lds_dwordx4 v132, s[44:45]
	s_add_i32 m0, s25, 0xe000
	s_nop 0
	s_add_u32 s98, s44, s0
	s_addc_u32 s99, s45, s1
	global_load_lds_dwordx4 v132, s[98:99]
	s_waitcnt vmcnt(8)
	s_waitcnt lgkmcnt(0)
	s_barrier
	s_setprio 1
	s_waitcnt lgkmcnt(0)
	v_mfma_f32_16x16x32_bf16 v[124:127], v[138:141], v[174:177], v[124:127]
	v_mfma_f32_16x16x32_bf16 v[120:123], v[146:149], v[174:177], v[120:123]
	v_mfma_f32_16x16x32_bf16 v[116:119], v[138:141], v[182:185], v[116:119]
	v_mfma_f32_16x16x32_bf16 v[112:115], v[146:149], v[182:185], v[112:115]
	v_mfma_f32_16x16x32_bf16 v[108:111], v[138:141], v[190:193], v[108:111]
	v_mfma_f32_16x16x32_bf16 v[104:107], v[146:149], v[190:193], v[104:107]
	v_mfma_f32_16x16x32_bf16 v[100:103], v[138:141], v[198:201], v[100:103]
	v_mfma_f32_16x16x32_bf16 v[96:99], v[146:149], v[198:201], v[96:99]
	v_mfma_f32_16x16x32_bf16 v[124:127], v[142:145], v[178:181], v[124:127]
	v_mfma_f32_16x16x32_bf16 v[120:123], v[154:157], v[178:181], v[120:123]
	v_mfma_f32_16x16x32_bf16 v[116:119], v[142:145], v[186:189], v[116:119]
	v_mfma_f32_16x16x32_bf16 v[112:115], v[154:157], v[186:189], v[112:115]
	v_mfma_f32_16x16x32_bf16 v[108:111], v[142:145], v[194:197], v[108:111]
	v_mfma_f32_16x16x32_bf16 v[104:107], v[154:157], v[194:197], v[104:107]
	v_mfma_f32_16x16x32_bf16 v[100:103], v[142:145], v[202:205], v[100:103]
	v_mfma_f32_16x16x32_bf16 v[96:99], v[154:157], v[202:205], v[96:99]
	s_setprio 0
	s_setprio 1
	v_mfma_f32_16x16x32_bf16 v[92:95], v[158:161], v[174:177], v[92:95]
	v_mfma_f32_16x16x32_bf16 v[88:91], v[166:169], v[174:177], v[88:91]
	v_mfma_f32_16x16x32_bf16 v[84:87], v[158:161], v[182:185], v[84:87]
	v_mfma_f32_16x16x32_bf16 v[80:83], v[166:169], v[182:185], v[80:83]
	v_mfma_f32_16x16x32_bf16 v[76:79], v[158:161], v[190:193], v[76:79]
	v_mfma_f32_16x16x32_bf16 v[72:75], v[166:169], v[190:193], v[72:75]
	v_mfma_f32_16x16x32_bf16 v[68:71], v[158:161], v[198:201], v[68:71]
	v_mfma_f32_16x16x32_bf16 v[64:67], v[166:169], v[198:201], v[64:67]
	v_mfma_f32_16x16x32_bf16 v[92:95], v[162:165], v[178:181], v[92:95]
	v_mfma_f32_16x16x32_bf16 v[88:91], v[170:173], v[178:181], v[88:91]
	v_mfma_f32_16x16x32_bf16 v[84:87], v[162:165], v[186:189], v[84:87]
	v_mfma_f32_16x16x32_bf16 v[80:83], v[170:173], v[186:189], v[80:83]
	v_mfma_f32_16x16x32_bf16 v[76:79], v[162:165], v[194:197], v[76:79]
	v_mfma_f32_16x16x32_bf16 v[72:75], v[170:173], v[194:197], v[72:75]
	v_mfma_f32_16x16x32_bf16 v[68:71], v[162:165], v[202:205], v[68:71]
	v_mfma_f32_16x16x32_bf16 v[64:67], v[170:173], v[202:205], v[64:67]
	s_setprio 0
	s_barrier
	s_add_i32 s47, s56, s24
	s_mov_b32 m0, s47
	ds_read_b128 v[174:177], v153 offset:16384
	ds_read_b128 v[178:181], v153 offset:17408
	ds_read_b128 v[182:185], v153 offset:18432
	ds_read_b128 v[186:189], v153 offset:19456
	ds_read_b128 v[190:193], v153 offset:20480
	ds_read_b128 v[194:197], v153 offset:21504
	ds_read_b128 v[198:201], v153 offset:22528
	ds_read_b128 v[202:205], v153 offset:23552
	global_load_lds_dwordx4 v130, s[66:67]
	s_add_i32 m0, s47, 0x2000
	s_add_i32 s47, s57, s24
	s_add_u32 s98, s66, s0
	s_addc_u32 s99, s67, s1
	global_load_lds_dwordx4 v130, s[98:99]
	s_mov_b32 m0, s47
	s_nop 0
	s_add_u32 s98, s66, s6
	s_addc_u32 s99, s67, s7
	global_load_lds_dwordx4 v130, s[98:99]
	s_add_i32 m0, s47, 0x2000
	s_nop 0
	s_add_u32 s98, s66, s8
	s_addc_u32 s99, s67, s9
	global_load_lds_dwordx4 v130, s[98:99]
	s_mov_b64 s[100:101], s[64:65]
	s_mov_b32 m0, s25
	s_nop 0
	global_load_lds_dwordx4 v128, s[64:65]
	s_mov_b32 m0, s33
	s_nop 0
	s_add_u32 s98, s64, s0
	s_addc_u32 s99, s65, s1
	global_load_lds_dwordx4 v128, s[98:99]
	s_waitcnt vmcnt(8)
	s_waitcnt lgkmcnt(0)
	s_barrier
	s_setprio 1
	s_waitcnt lgkmcnt(0)
	v_mfma_f32_16x16x32_bf16 v[60:63], v[138:141], v[174:177], v[60:63]
	v_mfma_f32_16x16x32_bf16 v[56:59], v[146:149], v[174:177], v[56:59]
	v_mfma_f32_16x16x32_bf16 v[52:55], v[138:141], v[182:185], v[52:55]
	v_mfma_f32_16x16x32_bf16 v[48:51], v[146:149], v[182:185], v[48:51]
	v_mfma_f32_16x16x32_bf16 v[44:47], v[138:141], v[190:193], v[44:47]
	v_mfma_f32_16x16x32_bf16 v[40:43], v[146:149], v[190:193], v[40:43]
	v_mfma_f32_16x16x32_bf16 v[36:39], v[138:141], v[198:201], v[36:39]
	v_mfma_f32_16x16x32_bf16 v[32:35], v[146:149], v[198:201], v[32:35]
	v_mfma_f32_16x16x32_bf16 v[60:63], v[142:145], v[178:181], v[60:63]
	v_mfma_f32_16x16x32_bf16 v[56:59], v[154:157], v[178:181], v[56:59]
	v_mfma_f32_16x16x32_bf16 v[52:55], v[142:145], v[186:189], v[52:55]
	v_mfma_f32_16x16x32_bf16 v[48:51], v[154:157], v[186:189], v[48:51]
	v_mfma_f32_16x16x32_bf16 v[44:47], v[142:145], v[194:197], v[44:47]
	v_mfma_f32_16x16x32_bf16 v[40:43], v[154:157], v[194:197], v[40:43]
	v_mfma_f32_16x16x32_bf16 v[36:39], v[142:145], v[202:205], v[36:39]
	v_mfma_f32_16x16x32_bf16 v[32:35], v[154:157], v[202:205], v[32:35]
	s_setprio 0
	s_setprio 1
	v_mfma_f32_16x16x32_bf16 v[28:31], v[158:161], v[174:177], v[28:31]
	v_mfma_f32_16x16x32_bf16 v[24:27], v[166:169], v[174:177], v[24:27]
	v_mfma_f32_16x16x32_bf16 v[20:23], v[158:161], v[182:185], v[20:23]
	v_mfma_f32_16x16x32_bf16 v[16:19], v[166:169], v[182:185], v[16:19]
	v_mfma_f32_16x16x32_bf16 v[12:15], v[158:161], v[190:193], v[12:15]
	v_mfma_f32_16x16x32_bf16 v[8:11], v[166:169], v[190:193], v[8:11]
	v_mfma_f32_16x16x32_bf16 v[4:7], v[158:161], v[198:201], v[4:7]
	v_mfma_f32_16x16x32_bf16 v[0:3], v[166:169], v[198:201], v[0:3]
	v_mfma_f32_16x16x32_bf16 v[28:31], v[162:165], v[178:181], v[28:31]
	v_mfma_f32_16x16x32_bf16 v[24:27], v[170:173], v[178:181], v[24:27]
	v_mfma_f32_16x16x32_bf16 v[20:23], v[162:165], v[186:189], v[20:23]
	v_mfma_f32_16x16x32_bf16 v[16:19], v[170:173], v[186:189], v[16:19]
	v_mfma_f32_16x16x32_bf16 v[12:15], v[162:165], v[194:197], v[12:15]
	v_mfma_f32_16x16x32_bf16 v[8:11], v[170:173], v[194:197], v[8:11]
	v_mfma_f32_16x16x32_bf16 v[4:7], v[162:165], v[202:205], v[4:7]
	v_mfma_f32_16x16x32_bf16 v[0:3], v[170:173], v[202:205], v[0:3]
	s_setprio 0
	s_barrier
	s_add_i32 s47, 0, 0x18000
	s_add_i32 s64, 0, 0x1c000
	v_add_u32_e32 v154, s47, v150
	v_add_u32_e32 v170, s64, v150
	ds_read_b128 v[138:141], v154
	ds_read_b128 v[142:145], v154 offset:1024
	ds_read_b128 v[146:149], v154 offset:2048
	ds_read_b128 v[154:157], v154 offset:3072
	ds_read_b128 v[158:161], v170
	ds_read_b128 v[162:165], v170 offset:1024
	ds_read_b128 v[166:169], v170 offset:2048
	ds_read_b128 v[170:173], v170 offset:3072
	s_mov_b32 m0, s48
	ds_read_b128 v[174:177], v153 offset:32768
	ds_read_b128 v[178:181], v153 offset:33792
	ds_read_b128 v[182:185], v153 offset:34816
	ds_read_b128 v[186:189], v153 offset:35840
	ds_read_b128 v[190:193], v153 offset:36864
	ds_read_b128 v[194:197], v153 offset:37888
	ds_read_b128 v[198:201], v153 offset:38912
	ds_read_b128 v[202:205], v153 offset:39936
	s_add_u32 s98, s100, s6
	s_addc_u32 s99, s101, s7
	global_load_lds_dwordx4 v128, s[98:99]
	s_mov_b32 m0, s49
	s_nop 0
	s_add_u32 s98, s100, s8
	s_addc_u32 s99, s101, s9
	global_load_lds_dwordx4 v128, s[98:99]
	s_waitcnt vmcnt(8)
	s_waitcnt lgkmcnt(0)
	s_barrier
	s_setprio 1
	s_waitcnt lgkmcnt(0)
	v_mfma_f32_16x16x32_bf16 v[124:127], v[138:141], v[174:177], v[124:127]
	v_mfma_f32_16x16x32_bf16 v[120:123], v[146:149], v[174:177], v[120:123]
	v_mfma_f32_16x16x32_bf16 v[116:119], v[138:141], v[182:185], v[116:119]
	v_mfma_f32_16x16x32_bf16 v[112:115], v[146:149], v[182:185], v[112:115]
	v_mfma_f32_16x16x32_bf16 v[108:111], v[138:141], v[190:193], v[108:111]
	v_mfma_f32_16x16x32_bf16 v[104:107], v[146:149], v[190:193], v[104:107]
	v_mfma_f32_16x16x32_bf16 v[100:103], v[138:141], v[198:201], v[100:103]
	v_mfma_f32_16x16x32_bf16 v[96:99], v[146:149], v[198:201], v[96:99]
	v_mfma_f32_16x16x32_bf16 v[124:127], v[142:145], v[178:181], v[124:127]
	v_mfma_f32_16x16x32_bf16 v[120:123], v[154:157], v[178:181], v[120:123]
	v_mfma_f32_16x16x32_bf16 v[116:119], v[142:145], v[186:189], v[116:119]
	v_mfma_f32_16x16x32_bf16 v[112:115], v[154:157], v[186:189], v[112:115]
	v_mfma_f32_16x16x32_bf16 v[108:111], v[142:145], v[194:197], v[108:111]
	v_mfma_f32_16x16x32_bf16 v[104:107], v[154:157], v[194:197], v[104:107]
	v_mfma_f32_16x16x32_bf16 v[100:103], v[142:145], v[202:205], v[100:103]
	v_mfma_f32_16x16x32_bf16 v[96:99], v[154:157], v[202:205], v[96:99]
	s_setprio 0
	s_setprio 1
	v_mfma_f32_16x16x32_bf16 v[92:95], v[158:161], v[174:177], v[92:95]
	v_mfma_f32_16x16x32_bf16 v[88:91], v[166:169], v[174:177], v[88:91]
	v_mfma_f32_16x16x32_bf16 v[84:87], v[158:161], v[182:185], v[84:87]
	v_mfma_f32_16x16x32_bf16 v[80:83], v[166:169], v[182:185], v[80:83]
	v_mfma_f32_16x16x32_bf16 v[76:79], v[158:161], v[190:193], v[76:79]
	v_mfma_f32_16x16x32_bf16 v[72:75], v[166:169], v[190:193], v[72:75]
	v_mfma_f32_16x16x32_bf16 v[68:71], v[158:161], v[198:201], v[68:71]
	v_mfma_f32_16x16x32_bf16 v[64:67], v[166:169], v[198:201], v[64:67]
	v_mfma_f32_16x16x32_bf16 v[92:95], v[162:165], v[178:181], v[92:95]
	v_mfma_f32_16x16x32_bf16 v[88:91], v[170:173], v[178:181], v[88:91]
	v_mfma_f32_16x16x32_bf16 v[84:87], v[162:165], v[186:189], v[84:87]
	v_mfma_f32_16x16x32_bf16 v[80:83], v[170:173], v[186:189], v[80:83]
	v_mfma_f32_16x16x32_bf16 v[76:79], v[162:165], v[194:197], v[76:79]
	v_mfma_f32_16x16x32_bf16 v[72:75], v[170:173], v[194:197], v[72:75]
	v_mfma_f32_16x16x32_bf16 v[68:71], v[162:165], v[202:205], v[68:71]
	v_mfma_f32_16x16x32_bf16 v[64:67], v[170:173], v[202:205], v[64:67]
	s_setprio 0
	s_barrier
	s_add_i32 s47, s47, s24
	s_mov_b32 m0, s47
	ds_read_b128 v[174:177], v153 offset:49152
	ds_read_b128 v[178:181], v153 offset:50176
	ds_read_b128 v[182:185], v153 offset:51200
	ds_read_b128 v[186:189], v153 offset:52224
	ds_read_b128 v[190:193], v153 offset:53248
	ds_read_b128 v[194:197], v153 offset:54272
	ds_read_b128 v[198:201], v153 offset:55296
	ds_read_b128 v[202:205], v153 offset:56320
	s_add_u32 s98, s66, s16
	s_addc_u32 s99, s67, s17
	global_load_lds_dwordx4 v130, s[98:99]
	s_add_i32 m0, s47, 0x2000
	s_add_i32 s47, s64, s24
	s_add_u32 s98, s66, s20
	s_addc_u32 s99, s67, s21
	global_load_lds_dwordx4 v130, s[98:99]
	s_mov_b32 m0, s47
	s_add_u32 s98, s66, s34
	s_addc_u32 s99, s67, s35
	global_load_lds_dwordx4 v130, s[98:99]
	s_add_i32 m0, s47, 0x2000
	s_nop 0
	s_add_u32 s98, s66, s36
	s_addc_u32 s99, s67, s37
	global_load_lds_dwordx4 v130, s[98:99]
	s_mov_b32 m0, s51
	s_nop 0
	s_add_u32 s98, s100, s16
	s_addc_u32 s99, s101, s17
	global_load_lds_dwordx4 v128, s[98:99]
	s_mov_b32 m0, s52
	s_nop 0
	s_add_u32 s98, s100, s20
	s_addc_u32 s99, s101, s21
	global_load_lds_dwordx4 v128, s[98:99]
	s_waitcnt vmcnt(8)
	s_waitcnt lgkmcnt(0)
	s_barrier
	s_setprio 1
	s_waitcnt lgkmcnt(0)
	v_mfma_f32_16x16x32_bf16 v[60:63], v[138:141], v[174:177], v[60:63]
	v_mfma_f32_16x16x32_bf16 v[56:59], v[146:149], v[174:177], v[56:59]
	v_mfma_f32_16x16x32_bf16 v[52:55], v[138:141], v[182:185], v[52:55]
	v_mfma_f32_16x16x32_bf16 v[48:51], v[146:149], v[182:185], v[48:51]
	v_mfma_f32_16x16x32_bf16 v[44:47], v[138:141], v[190:193], v[44:47]
	v_mfma_f32_16x16x32_bf16 v[40:43], v[146:149], v[190:193], v[40:43]
	v_mfma_f32_16x16x32_bf16 v[36:39], v[138:141], v[198:201], v[36:39]
	v_mfma_f32_16x16x32_bf16 v[32:35], v[146:149], v[198:201], v[32:35]
	v_mfma_f32_16x16x32_bf16 v[60:63], v[142:145], v[178:181], v[60:63]
	v_mfma_f32_16x16x32_bf16 v[56:59], v[154:157], v[178:181], v[56:59]
	v_mfma_f32_16x16x32_bf16 v[52:55], v[142:145], v[186:189], v[52:55]
	v_mfma_f32_16x16x32_bf16 v[48:51], v[154:157], v[186:189], v[48:51]
	v_mfma_f32_16x16x32_bf16 v[44:47], v[142:145], v[194:197], v[44:47]
	v_mfma_f32_16x16x32_bf16 v[40:43], v[154:157], v[194:197], v[40:43]
	v_mfma_f32_16x16x32_bf16 v[36:39], v[142:145], v[202:205], v[36:39]
	v_mfma_f32_16x16x32_bf16 v[32:35], v[154:157], v[202:205], v[32:35]
	s_setprio 0
	s_setprio 1
	v_mfma_f32_16x16x32_bf16 v[28:31], v[158:161], v[174:177], v[28:31]
	v_mfma_f32_16x16x32_bf16 v[24:27], v[166:169], v[174:177], v[24:27]
	v_mfma_f32_16x16x32_bf16 v[20:23], v[158:161], v[182:185], v[20:23]
	v_mfma_f32_16x16x32_bf16 v[16:19], v[166:169], v[182:185], v[16:19]
	v_mfma_f32_16x16x32_bf16 v[12:15], v[158:161], v[190:193], v[12:15]
	v_mfma_f32_16x16x32_bf16 v[8:11], v[166:169], v[190:193], v[8:11]
	v_mfma_f32_16x16x32_bf16 v[4:7], v[158:161], v[198:201], v[4:7]
	v_mfma_f32_16x16x32_bf16 v[0:3], v[166:169], v[198:201], v[0:3]
	v_mfma_f32_16x16x32_bf16 v[28:31], v[162:165], v[178:181], v[28:31]
	v_mfma_f32_16x16x32_bf16 v[24:27], v[170:173], v[178:181], v[24:27]
	v_mfma_f32_16x16x32_bf16 v[20:23], v[162:165], v[186:189], v[20:23]
	v_mfma_f32_16x16x32_bf16 v[16:19], v[170:173], v[186:189], v[16:19]
	v_mfma_f32_16x16x32_bf16 v[12:15], v[162:165], v[194:197], v[12:15]
	v_mfma_f32_16x16x32_bf16 v[8:11], v[170:173], v[194:197], v[8:11]
	v_mfma_f32_16x16x32_bf16 v[4:7], v[162:165], v[202:205], v[4:7]
	v_mfma_f32_16x16x32_bf16 v[0:3], v[170:173], v[202:205], v[0:3]
	s_setprio 0
	s_barrier
	s_add_i32 s46, s46, 2
	s_add_u32 s62, s62, 0x100
	s_addc_u32 s63, s63, 0
	s_add_u32 s44, s44, 0x100
	s_addc_u32 s45, s45, 0
	s_cmpk_gt_u32 s46, 0xa9
	s_cbranch_scc0 .LBB0_1034
	s_and_b64 vcc, exec, s[38:39]
	s_cbranch_vccz .LBB0_1037
	s_barrier

.LBB0_1180:
	ds_read_b128 v[112:115], v181
	ds_read_b128 v[116:119], v181 offset:1024
	ds_read_b128 v[128:131], v181 offset:2048
	ds_read_b128 v[142:145], v181 offset:3072
	ds_read_b128 v[146:149], v202
	ds_read_b128 v[150:153], v202 offset:1024
	ds_read_b128 v[154:157], v202 offset:2048
	ds_read_b128 v[168:171], v202 offset:3072
	s_add_u32 s49, s46, 0xfff80080
	s_addc_u32 s70, s47, -1
	s_cmp_eq_u32 s48, 28
	s_cselect_b32 s71, s39, s70
	s_cselect_b32 s70, s66, s49
	s_cselect_b32 s73, s37, s69
	s_cselect_b32 s72, s67, s68
	s_add_i32 m0, s45, 0xc000
	ds_read_b128 v[172:175], v203
	ds_read_b128 v[182:185], v203 offset:1024
	ds_read_b128 v[186:189], v203 offset:2048
	ds_read_b128 v[190:193], v203 offset:3072
	ds_read_b128 v[194:197], v203 offset:4096
	ds_read_b128 v[198:201], v203 offset:5120
	ds_read_b128 v[206:209], v203 offset:6144
	ds_read_b128 v[210:213], v203 offset:7168
	global_load_lds_dwordx4 v162, s[46:47]
	s_add_i32 m0, s45, 0xe000
	s_nop 0
	s_add_u32 s98, s46, s2
	s_addc_u32 s99, s47, s3
	global_load_lds_dwordx4 v162, s[98:99]
	s_waitcnt vmcnt(8)
	s_waitcnt lgkmcnt(0)
	s_barrier
	s_setprio 1
	s_waitcnt lgkmcnt(0)
	v_mfma_i32_16x16x64_i8 v[138:141], v[112:115], v[172:175], v[138:141]
	v_mfma_i32_16x16x64_i8 v[132:135], v[128:131], v[172:175], v[134:137]
	v_mfma_i32_16x16x64_i8 v[124:127], v[112:115], v[186:189], v[124:127]
	v_mfma_i32_16x16x64_i8 v[120:123], v[128:131], v[186:189], v[120:123]
	v_mfma_i32_16x16x64_i8 v[108:111], v[112:115], v[194:197], v[108:111]
	v_mfma_i32_16x16x64_i8 v[104:107], v[128:131], v[194:197], v[104:107]
	v_mfma_i32_16x16x64_i8 v[100:103], v[112:115], v[206:209], v[100:103]
	v_mfma_i32_16x16x64_i8 v[96:99], v[128:131], v[206:209], v[96:99]
	v_mfma_i32_16x16x64_i8 v[138:141], v[116:119], v[182:185], v[138:141]
	v_mfma_i32_16x16x64_i8 v[132:135], v[142:145], v[182:185], v[132:135]
	v_mfma_i32_16x16x64_i8 v[124:127], v[116:119], v[190:193], v[124:127]
	v_mfma_i32_16x16x64_i8 v[120:123], v[142:145], v[190:193], v[120:123]
	v_mfma_i32_16x16x64_i8 v[108:111], v[116:119], v[198:201], v[108:111]
	v_mfma_i32_16x16x64_i8 v[104:107], v[142:145], v[198:201], v[104:107]
	v_mfma_i32_16x16x64_i8 v[100:103], v[116:119], v[210:213], v[100:103]
	v_mfma_i32_16x16x64_i8 v[96:99], v[142:145], v[210:213], v[96:99]
	s_setprio 0
	s_setprio 1
	v_mfma_i32_16x16x64_i8 v[60:63], v[146:149], v[172:175], v[60:63]
	v_mfma_i32_16x16x64_i8 v[56:59], v[154:157], v[172:175], v[56:59]
	v_mfma_i32_16x16x64_i8 v[52:55], v[146:149], v[186:189], v[52:55]
	v_mfma_i32_16x16x64_i8 v[48:51], v[154:157], v[186:189], v[48:51]
	v_mfma_i32_16x16x64_i8 v[44:47], v[146:149], v[194:197], v[44:47]
	v_mfma_i32_16x16x64_i8 v[40:43], v[154:157], v[194:197], v[40:43]
	v_mfma_i32_16x16x64_i8 v[36:39], v[146:149], v[206:209], v[36:39]
	v_mfma_i32_16x16x64_i8 v[32:35], v[154:157], v[206:209], v[32:35]
	v_mfma_i32_16x16x64_i8 v[60:63], v[150:153], v[182:185], v[60:63]
	v_mfma_i32_16x16x64_i8 v[56:59], v[168:171], v[182:185], v[56:59]
	v_mfma_i32_16x16x64_i8 v[52:55], v[150:153], v[190:193], v[52:55]
	v_mfma_i32_16x16x64_i8 v[48:51], v[168:171], v[190:193], v[48:51]
	v_mfma_i32_16x16x64_i8 v[44:47], v[150:153], v[198:201], v[44:47]
	v_mfma_i32_16x16x64_i8 v[40:43], v[168:171], v[198:201], v[40:43]
	v_mfma_i32_16x16x64_i8 v[36:39], v[150:153], v[210:213], v[36:39]
	v_mfma_i32_16x16x64_i8 v[32:35], v[168:171], v[210:213], v[32:35]
	s_setprio 0
	s_barrier
	s_add_i32 s49, s61, s33
	s_mov_b32 m0, s49
	ds_read_b128 v[172:175], v203 offset:16384
	ds_read_b128 v[182:185], v203 offset:17408
	ds_read_b128 v[186:189], v203 offset:18432
	ds_read_b128 v[190:193], v203 offset:19456
	ds_read_b128 v[194:197], v203 offset:20480
	ds_read_b128 v[198:201], v203 offset:21504
	ds_read_b128 v[206:209], v203 offset:22528
	ds_read_b128 v[210:213], v203 offset:23552
	global_load_lds_dwordx4 v160, s[72:73]
	s_add_i32 m0, s49, 0x2000
	s_add_i32 s49, s62, s33
	s_add_u32 s98, s72, s2
	s_addc_u32 s99, s73, s3
	global_load_lds_dwordx4 v160, s[98:99]
	s_mov_b32 m0, s49
	s_mov_b64 s[100:101], s[70:71]
	s_add_u32 s98, s72, s6
	s_addc_u32 s99, s73, s7
	global_load_lds_dwordx4 v160, s[98:99]
	s_add_i32 m0, s49, 0x2000
	s_nop 0
	s_add_u32 s98, s72, s8
	s_addc_u32 s99, s73, s9
	global_load_lds_dwordx4 v160, s[98:99]
	s_mov_b32 m0, s45
	s_nop 0
	global_load_lds_dwordx4 v158, s[70:71]
	s_mov_b32 m0, s50
	s_nop 0
	s_add_u32 s98, s70, s2
	s_addc_u32 s99, s71, s3
	global_load_lds_dwordx4 v158, s[98:99]
	s_waitcnt vmcnt(8)
	s_waitcnt lgkmcnt(0)
	s_barrier
	s_setprio 1
	s_waitcnt lgkmcnt(0)
	v_mfma_i32_16x16x64_i8 v[92:95], v[112:115], v[172:175], v[92:95]
	v_mfma_i32_16x16x64_i8 v[88:91], v[128:131], v[172:175], v[88:91]
	v_mfma_i32_16x16x64_i8 v[84:87], v[112:115], v[186:189], v[84:87]
	v_mfma_i32_16x16x64_i8 v[80:83], v[128:131], v[186:189], v[80:83]
	v_mfma_i32_16x16x64_i8 v[76:79], v[112:115], v[194:197], v[76:79]
	v_mfma_i32_16x16x64_i8 v[72:75], v[128:131], v[194:197], v[72:75]
	v_mfma_i32_16x16x64_i8 v[68:71], v[112:115], v[206:209], v[68:71]
	v_mfma_i32_16x16x64_i8 v[64:67], v[128:131], v[206:209], v[64:67]
	v_mfma_i32_16x16x64_i8 v[92:95], v[116:119], v[182:185], v[92:95]
	v_mfma_i32_16x16x64_i8 v[88:91], v[142:145], v[182:185], v[88:91]
	v_mfma_i32_16x16x64_i8 v[84:87], v[116:119], v[190:193], v[84:87]
	v_mfma_i32_16x16x64_i8 v[80:83], v[142:145], v[190:193], v[80:83]
	v_mfma_i32_16x16x64_i8 v[76:79], v[116:119], v[198:201], v[76:79]
	v_mfma_i32_16x16x64_i8 v[72:75], v[142:145], v[198:201], v[72:75]
	v_mfma_i32_16x16x64_i8 v[68:71], v[116:119], v[210:213], v[68:71]
	v_mfma_i32_16x16x64_i8 v[64:67], v[142:145], v[210:213], v[64:67]
	s_setprio 0
	s_setprio 1
	v_mfma_i32_16x16x64_i8 v[28:31], v[146:149], v[172:175], v[28:31]
	v_mfma_i32_16x16x64_i8 v[24:27], v[154:157], v[172:175], v[24:27]
	v_mfma_i32_16x16x64_i8 v[20:23], v[146:149], v[186:189], v[20:23]
	v_mfma_i32_16x16x64_i8 v[16:19], v[154:157], v[186:189], v[16:19]
	v_mfma_i32_16x16x64_i8 v[12:15], v[146:149], v[194:197], v[12:15]
	v_mfma_i32_16x16x64_i8 v[8:11], v[154:157], v[194:197], v[8:11]
	v_mfma_i32_16x16x64_i8 v[4:7], v[146:149], v[206:209], v[4:7]
	v_mfma_i32_16x16x64_i8 v[0:3], v[154:157], v[206:209], v[0:3]
	v_mfma_i32_16x16x64_i8 v[28:31], v[150:153], v[182:185], v[28:31]
	v_mfma_i32_16x16x64_i8 v[24:27], v[168:171], v[182:185], v[24:27]
	v_mfma_i32_16x16x64_i8 v[20:23], v[150:153], v[190:193], v[20:23]
	v_mfma_i32_16x16x64_i8 v[16:19], v[168:171], v[190:193], v[16:19]
	v_mfma_i32_16x16x64_i8 v[12:15], v[150:153], v[198:201], v[12:15]
	v_mfma_i32_16x16x64_i8 v[8:11], v[168:171], v[198:201], v[8:11]
	v_mfma_i32_16x16x64_i8 v[4:7], v[150:153], v[210:213], v[4:7]
	v_mfma_i32_16x16x64_i8 v[0:3], v[168:171], v[210:213], v[0:3]
	s_setprio 0
	s_barrier
	s_add_i32 s49, 0, 0x18000
	v_add_u32_e32 v136, s49, v179
	s_add_i32 s70, 0, 0x1c000
	ds_read_b128 v[112:115], v136
	ds_read_b128 v[116:119], v136 offset:1024
	ds_read_b128 v[128:131], v136 offset:2048
	ds_read_b128 v[142:145], v136 offset:3072
	v_add_u32_e32 v136, s70, v179
	ds_read_b128 v[146:149], v136
	ds_read_b128 v[150:153], v136 offset:1024
	ds_read_b128 v[154:157], v136 offset:2048
	ds_read_b128 v[168:171], v136 offset:3072
	s_mov_b32 m0, s51
	ds_read_b128 v[172:175], v203 offset:32768
	ds_read_b128 v[182:185], v203 offset:33792
	ds_read_b128 v[186:189], v203 offset:34816
	ds_read_b128 v[190:193], v203 offset:35840
	ds_read_b128 v[194:197], v203 offset:36864
	ds_read_b128 v[198:201], v203 offset:37888
	ds_read_b128 v[206:209], v203 offset:38912
	ds_read_b128 v[210:213], v203 offset:39936
	s_add_u32 s98, s100, s6
	s_addc_u32 s99, s101, s7
	global_load_lds_dwordx4 v158, s[98:99]
	s_mov_b32 m0, s52
	s_nop 0
	s_add_u32 s98, s100, s8
	s_addc_u32 s99, s101, s9
	global_load_lds_dwordx4 v158, s[98:99]
	s_waitcnt vmcnt(8)
	s_waitcnt lgkmcnt(0)
	s_barrier
	s_setprio 1
	s_waitcnt lgkmcnt(0)
	v_mfma_i32_16x16x64_i8 v[136:139], v[112:115], v[172:175], v[138:141]
	v_mfma_i32_16x16x64_i8 v[132:135], v[128:131], v[172:175], v[132:135]
	v_mfma_i32_16x16x64_i8 v[124:127], v[112:115], v[186:189], v[124:127]
	v_mfma_i32_16x16x64_i8 v[120:123], v[128:131], v[186:189], v[120:123]
	v_mfma_i32_16x16x64_i8 v[108:111], v[112:115], v[194:197], v[108:111]
	v_mfma_i32_16x16x64_i8 v[104:107], v[128:131], v[194:197], v[104:107]
	v_mfma_i32_16x16x64_i8 v[100:103], v[112:115], v[206:209], v[100:103]
	v_mfma_i32_16x16x64_i8 v[96:99], v[128:131], v[206:209], v[96:99]
	v_mfma_i32_16x16x64_i8 v[138:141], v[116:119], v[182:185], v[136:139]
	v_mfma_i32_16x16x64_i8 v[134:137], v[142:145], v[182:185], v[132:135]
	v_mfma_i32_16x16x64_i8 v[124:127], v[116:119], v[190:193], v[124:127]
	v_mfma_i32_16x16x64_i8 v[120:123], v[142:145], v[190:193], v[120:123]
	v_mfma_i32_16x16x64_i8 v[108:111], v[116:119], v[198:201], v[108:111]
	v_mfma_i32_16x16x64_i8 v[104:107], v[142:145], v[198:201], v[104:107]
	v_mfma_i32_16x16x64_i8 v[100:103], v[116:119], v[210:213], v[100:103]
	v_mfma_i32_16x16x64_i8 v[96:99], v[142:145], v[210:213], v[96:99]
	s_setprio 0
	s_setprio 1
	v_mfma_i32_16x16x64_i8 v[60:63], v[146:149], v[172:175], v[60:63]
	v_mfma_i32_16x16x64_i8 v[56:59], v[154:157], v[172:175], v[56:59]
	v_mfma_i32_16x16x64_i8 v[52:55], v[146:149], v[186:189], v[52:55]
	v_mfma_i32_16x16x64_i8 v[48:51], v[154:157], v[186:189], v[48:51]
	v_mfma_i32_16x16x64_i8 v[44:47], v[146:149], v[194:197], v[44:47]
	v_mfma_i32_16x16x64_i8 v[40:43], v[154:157], v[194:197], v[40:43]
	v_mfma_i32_16x16x64_i8 v[36:39], v[146:149], v[206:209], v[36:39]
	v_mfma_i32_16x16x64_i8 v[32:35], v[154:157], v[206:209], v[32:35]
	v_mfma_i32_16x16x64_i8 v[60:63], v[150:153], v[182:185], v[60:63]
	v_mfma_i32_16x16x64_i8 v[56:59], v[168:171], v[182:185], v[56:59]
	v_mfma_i32_16x16x64_i8 v[52:55], v[150:153], v[190:193], v[52:55]
	v_mfma_i32_16x16x64_i8 v[48:51], v[168:171], v[190:193], v[48:51]
	v_mfma_i32_16x16x64_i8 v[44:47], v[150:153], v[198:201], v[44:47]
	v_mfma_i32_16x16x64_i8 v[40:43], v[168:171], v[198:201], v[40:43]
	v_mfma_i32_16x16x64_i8 v[36:39], v[150:153], v[210:213], v[36:39]
	v_mfma_i32_16x16x64_i8 v[32:35], v[168:171], v[210:213], v[32:35]
	s_setprio 0
	s_barrier
	s_add_i32 s49, s49, s33
	s_mov_b32 m0, s49
	ds_read_b128 v[172:175], v203 offset:49152
	ds_read_b128 v[182:185], v203 offset:50176
	ds_read_b128 v[186:189], v203 offset:51200
	ds_read_b128 v[190:193], v203 offset:52224
	ds_read_b128 v[194:197], v203 offset:53248
	ds_read_b128 v[198:201], v203 offset:54272
	ds_read_b128 v[206:209], v203 offset:55296
	ds_read_b128 v[210:213], v203 offset:56320
	s_add_u32 s98, s72, s16
	s_addc_u32 s99, s73, s17
	global_load_lds_dwordx4 v160, s[98:99]
	s_add_i32 m0, s49, 0x2000
	s_add_i32 s49, s70, s33
	s_add_u32 s98, s72, s18
	s_addc_u32 s99, s73, s19
	global_load_lds_dwordx4 v160, s[98:99]
	s_mov_b32 m0, s49
	s_nop 0
	s_add_u32 s98, s72, s20
	s_addc_u32 s99, s73, s21
	global_load_lds_dwordx4 v160, s[98:99]
	s_add_i32 m0, s49, 0x2000
	s_nop 0
	s_add_u32 s98, s72, s30
	s_addc_u32 s99, s73, s31
	global_load_lds_dwordx4 v160, s[98:99]
	s_mov_b32 m0, s54
	s_nop 0
	s_add_u32 s98, s100, s16
	s_addc_u32 s99, s101, s17
	global_load_lds_dwordx4 v158, s[98:99]
	s_mov_b32 m0, s55
	s_nop 0
	s_add_u32 s98, s100, s18
	s_addc_u32 s99, s101, s19
	global_load_lds_dwordx4 v158, s[98:99]
	s_waitcnt vmcnt(8)
	s_waitcnt lgkmcnt(0)
	s_barrier
	s_setprio 1
	s_waitcnt lgkmcnt(0)
	v_mfma_i32_16x16x64_i8 v[92:95], v[112:115], v[172:175], v[92:95]
	v_mfma_i32_16x16x64_i8 v[88:91], v[128:131], v[172:175], v[88:91]
	v_mfma_i32_16x16x64_i8 v[84:87], v[112:115], v[186:189], v[84:87]
	v_mfma_i32_16x16x64_i8 v[80:83], v[128:131], v[186:189], v[80:83]
	v_mfma_i32_16x16x64_i8 v[76:79], v[112:115], v[194:197], v[76:79]
	v_mfma_i32_16x16x64_i8 v[72:75], v[128:131], v[194:197], v[72:75]
	v_mfma_i32_16x16x64_i8 v[68:71], v[112:115], v[206:209], v[68:71]
	v_mfma_i32_16x16x64_i8 v[64:67], v[128:131], v[206:209], v[64:67]
	v_mfma_i32_16x16x64_i8 v[92:95], v[116:119], v[182:185], v[92:95]
	v_mfma_i32_16x16x64_i8 v[88:91], v[142:145], v[182:185], v[88:91]
	v_mfma_i32_16x16x64_i8 v[84:87], v[116:119], v[190:193], v[84:87]
	v_mfma_i32_16x16x64_i8 v[80:83], v[142:145], v[190:193], v[80:83]
	v_mfma_i32_16x16x64_i8 v[76:79], v[116:119], v[198:201], v[76:79]
	v_mfma_i32_16x16x64_i8 v[72:75], v[142:145], v[198:201], v[72:75]
	v_mfma_i32_16x16x64_i8 v[68:71], v[116:119], v[210:213], v[68:71]
	v_mfma_i32_16x16x64_i8 v[64:67], v[142:145], v[210:213], v[64:67]
	s_setprio 0
	s_setprio 1
	v_mfma_i32_16x16x64_i8 v[28:31], v[146:149], v[172:175], v[28:31]
	v_mfma_i32_16x16x64_i8 v[24:27], v[154:157], v[172:175], v[24:27]
	v_mfma_i32_16x16x64_i8 v[20:23], v[146:149], v[186:189], v[20:23]
	v_mfma_i32_16x16x64_i8 v[16:19], v[154:157], v[186:189], v[16:19]
	v_mfma_i32_16x16x64_i8 v[12:15], v[146:149], v[194:197], v[12:15]
	v_mfma_i32_16x16x64_i8 v[8:11], v[154:157], v[194:197], v[8:11]
	v_mfma_i32_16x16x64_i8 v[4:7], v[146:149], v[206:209], v[4:7]
	v_mfma_i32_16x16x64_i8 v[0:3], v[154:157], v[206:209], v[0:3]
	v_mfma_i32_16x16x64_i8 v[28:31], v[150:153], v[182:185], v[28:31]
	v_mfma_i32_16x16x64_i8 v[24:27], v[168:171], v[182:185], v[24:27]
	v_mfma_i32_16x16x64_i8 v[20:23], v[150:153], v[190:193], v[20:23]
	v_mfma_i32_16x16x64_i8 v[16:19], v[168:171], v[190:193], v[16:19]
	v_mfma_i32_16x16x64_i8 v[12:15], v[150:153], v[198:201], v[12:15]
	v_mfma_i32_16x16x64_i8 v[8:11], v[168:171], v[198:201], v[8:11]
	v_mfma_i32_16x16x64_i8 v[4:7], v[150:153], v[210:213], v[4:7]
	v_mfma_i32_16x16x64_i8 v[0:3], v[168:171], v[210:213], v[0:3]
	s_setprio 0
	s_barrier
	s_add_i32 s48, s48, 2
	s_add_u32 s68, s68, 0x100
	s_addc_u32 s69, s69, 0
	s_add_u32 s46, s46, 0x100
	s_addc_u32 s47, s47, 0
	s_cmp_gt_u32 s48, 29
	s_cbranch_scc0 .LBB0_1180
	s_and_b64 vcc, exec, s[34:35]
	s_cbranch_vccz .LBB0_1183
	s_barrier

	.amdhsa_kernel _Z6mk_fwd4Args
		.amdhsa_group_segment_fixed_size 0
		.amdhsa_private_segment_fixed_size 0
		.amdhsa_kernarg_size 456
		.amdhsa_user_sgpr_count 2
		.amdhsa_user_sgpr_dispatch_ptr 0
		.amdhsa_user_sgpr_queue_ptr 0
		.amdhsa_user_sgpr_kernarg_segment_ptr 1
		.amdhsa_user_sgpr_dispatch_id 0
		.amdhsa_user_sgpr_kernarg_preload_length 0
		.amdhsa_user_sgpr_kernarg_preload_offset 0
		.amdhsa_user_sgpr_private_segment_size 0
		.amdhsa_uses_dynamic_stack 0
		.amdhsa_enable_private_segment 0
		.amdhsa_system_sgpr_workgroup_id_x 1
		.amdhsa_system_sgpr_workgroup_id_y 0
		.amdhsa_system_sgpr_workgroup_id_z 0
		.amdhsa_system_sgpr_workgroup_info 0
		.amdhsa_system_vgpr_workitem_id 0
		.amdhsa_next_free_vgpr 252
		.amdhsa_next_free_sgpr 102
		.amdhsa_accum_offset 252
		.amdhsa_reserve_vcc 1
		.amdhsa_float_round_mode_32 0
		.amdhsa_float_round_mode_16_64 0
		.amdhsa_float_denorm_mode_32 3
		.amdhsa_float_denorm_mode_16_64 3
		.amdhsa_dx10_clamp 1
		.amdhsa_ieee_mode 1
		.amdhsa_fp16_overflow 0
		.amdhsa_tg_split 0
		.amdhsa_exception_fp_ieee_invalid_op 0
		.amdhsa_exception_fp_denorm_src 0
		.amdhsa_exception_fp_ieee_div_zero 0
		.amdhsa_exception_fp_ieee_overflow 0
		.amdhsa_exception_fp_ieee_underflow 0
		.amdhsa_exception_fp_ieee_inexact 0
		.amdhsa_exception_int_div_zero 0
	.end_amdhsa_kernel

amdhsa.kernels:
  - .agpr_count:     0
    .args:
      - .offset:         0
        .size:           200
        .value_kind:     by_value
      - .offset:         200
        .size:           4
        .value_kind:     hidden_block_count_x
      - .offset:         204
        .size:           4
        .value_kind:     hidden_block_count_y
      - .offset:         208
        .size:           4
        .value_kind:     hidden_block_count_z
      - .offset:         212
        .size:           2
        .value_kind:     hidden_group_size_x
      - .offset:         214
        .size:           2
        .value_kind:     hidden_group_size_y
      - .offset:         216
        .size:           2
        .value_kind:     hidden_group_size_z
      - .offset:         218
        .size:           2
        .value_kind:     hidden_remainder_x
      - .offset:         220
        .size:           2
        .value_kind:     hidden_remainder_y
      - .offset:         222
        .size:           2
        .value_kind:     hidden_remainder_z
      - .offset:         240
        .size:           8
        .value_kind:     hidden_global_offset_x
      - .offset:         248
        .size:           8
        .value_kind:     hidden_global_offset_y
      - .offset:         256
        .size:           8
        .value_kind:     hidden_global_offset_z
      - .offset:         264
        .size:           2
        .value_kind:     hidden_grid_dims
      - .offset:         320
        .size:           4
        .value_kind:     hidden_dynamic_lds_size
    .group_segment_fixed_size: 0
    .kernarg_segment_align: 8
    .kernarg_segment_size: 456
    .language:       OpenCL C
    .language_version:
      - 2
      - 0
    .max_flat_workgroup_size: 512
    .name:           _Z6mk_fwd4Args
    .private_segment_fixed_size: 0
    .sgpr_count:     108
    .sgpr_spill_count: 118
    .symbol:         _Z6mk_fwd4Args.kd
    .uniform_work_group_size: 1
    .uses_dynamic_stack: false
    .vgpr_count:     252
    .vgpr_spill_count: 0
    .wavefront_size: 64
